# v6 plus: redundant post-barrier s_waitcnt lgkmcnt(0) removed from the MFMA segments of the five GEMM K-loops (lgkmcnt already drained before the barrier)
# baseline (speedup 1.0000x reference)
.LBB0_230:
	s_add_u32 s28, s0, 0xfff00080
	s_addc_u32 s29, s1, -1
	s_add_i32 s51, 0, 0x10000
	s_cmp_eq_u32 s50, 60
	s_cselect_b32 s31, s34, s29
	s_cselect_b32 s30, s35, s28
	v_add_u32_e32 v0, s51, v179
	s_cselect_b32 s29, s27, s43
	s_cselect_b32 s28, s40, s41
	s_add_i32 s77, 0, 0x14000
	ds_read_b128 v[130:133], v0
	ds_read_b128 v[134:137], v0 offset:1024
	ds_read_b128 v[138:141], v0 offset:2048
	ds_read_b128 v[142:145], v0 offset:3072
	v_add_u32_e32 v0, s77, v179
	ds_read_b128 v[146:149], v0
	ds_read_b128 v[150:153], v0 offset:1024
	ds_read_b128 v[154:157], v0 offset:2048
	ds_read_b128 v[158:161], v0 offset:3072
	v_lshl_add_u64 v[194:195], s[0:1], 0, v[170:171]
	s_add_i32 m0, s14, 0xc000
	ds_read_b128 v[174:177], v192
	ds_read_b128 v[180:183], v192 offset:1024
	ds_read_b128 v[184:187], v192 offset:2048
	ds_read_b128 v[188:191], v192 offset:3072
	ds_read_b128 v[200:203], v192 offset:4096
	ds_read_b128 v[204:207], v192 offset:5120
	ds_read_b128 v[208:211], v192 offset:6144
	ds_read_b128 v[212:215], v192 offset:7168
	global_load_lds_dwordx4 v[194:195], off
	v_lshl_add_u64 v[194:195], s[0:1], 0, v[172:173]
	s_add_i32 m0, s14, 0xe000
	s_nop 0
	global_load_lds_dwordx4 v[194:195], off
	s_waitcnt vmcnt(8)
	s_waitcnt lgkmcnt(0)
	s_barrier
	v_mfma_f32_16x16x32_bf16 v[126:129], v[130:133], v[174:177], v[126:129]
	v_mfma_f32_16x16x32_bf16 v[122:125], v[138:141], v[174:177], v[122:125]
	v_mfma_f32_16x16x32_bf16 v[110:113], v[130:133], v[184:187], v[110:113]
	v_mfma_f32_16x16x32_bf16 v[106:109], v[138:141], v[184:187], v[106:109]
	v_mfma_f32_16x16x32_bf16 v[94:97], v[130:133], v[200:203], v[94:97]
	v_mfma_f32_16x16x32_bf16 v[90:93], v[138:141], v[200:203], v[90:93]
	v_mfma_f32_16x16x32_bf16 v[78:81], v[130:133], v[208:211], v[78:81]
	v_mfma_f32_16x16x32_bf16 v[74:77], v[138:141], v[208:211], v[74:77]
	v_mfma_f32_16x16x32_bf16 v[126:129], v[134:137], v[180:183], v[126:129]
	v_mfma_f32_16x16x32_bf16 v[122:125], v[142:145], v[180:183], v[122:125]
	v_mfma_f32_16x16x32_bf16 v[110:113], v[134:137], v[188:191], v[110:113]
	v_mfma_f32_16x16x32_bf16 v[106:109], v[142:145], v[188:191], v[106:109]
	v_mfma_f32_16x16x32_bf16 v[94:97], v[134:137], v[204:207], v[94:97]
	v_mfma_f32_16x16x32_bf16 v[90:93], v[142:145], v[204:207], v[90:93]
	v_mfma_f32_16x16x32_bf16 v[78:81], v[134:137], v[212:215], v[78:81]
	v_mfma_f32_16x16x32_bf16 v[74:77], v[142:145], v[212:215], v[74:77]
	v_mfma_f32_16x16x32_bf16 v[118:121], v[146:149], v[174:177], v[118:121]
	v_mfma_f32_16x16x32_bf16 v[114:117], v[154:157], v[174:177], v[114:117]
	v_mfma_f32_16x16x32_bf16 v[102:105], v[146:149], v[184:187], v[102:105]
	v_mfma_f32_16x16x32_bf16 v[98:101], v[154:157], v[184:187], v[98:101]
	v_mfma_f32_16x16x32_bf16 v[86:89], v[146:149], v[200:203], v[86:89]
	v_mfma_f32_16x16x32_bf16 v[82:85], v[154:157], v[200:203], v[82:85]
	v_mfma_f32_16x16x32_bf16 v[70:73], v[146:149], v[208:211], v[70:73]
	v_mfma_f32_16x16x32_bf16 v[66:69], v[154:157], v[208:211], v[66:69]
	v_mfma_f32_16x16x32_bf16 v[118:121], v[150:153], v[180:183], v[118:121]
	v_mfma_f32_16x16x32_bf16 v[114:117], v[158:161], v[180:183], v[114:117]
	v_mfma_f32_16x16x32_bf16 v[102:105], v[150:153], v[188:191], v[102:105]
	v_mfma_f32_16x16x32_bf16 v[98:101], v[158:161], v[188:191], v[98:101]
	v_mfma_f32_16x16x32_bf16 v[86:89], v[150:153], v[204:207], v[86:89]
	v_mfma_f32_16x16x32_bf16 v[82:85], v[158:161], v[204:207], v[82:85]
	v_mfma_f32_16x16x32_bf16 v[70:73], v[150:153], v[212:215], v[70:73]
	v_mfma_f32_16x16x32_bf16 v[66:69], v[158:161], v[212:215], v[66:69]
	s_barrier
	s_add_i32 s51, s51, s9
	v_lshl_add_u64 v[194:195], s[28:29], 0, v[166:167]
	s_mov_b32 m0, s51
	ds_read_b128 v[174:177], v192 offset:16384
	ds_read_b128 v[180:183], v192 offset:17408
	ds_read_b128 v[184:187], v192 offset:18432
	ds_read_b128 v[188:191], v192 offset:19456
	ds_read_b128 v[200:203], v192 offset:20480
	ds_read_b128 v[204:207], v192 offset:21504
	ds_read_b128 v[208:211], v192 offset:22528
	ds_read_b128 v[212:215], v192 offset:23552
	global_load_lds_dwordx4 v[194:195], off
	s_add_i32 m0, s51, 0x2000
	s_add_u32 s80, s28, 0x100000
	v_lshl_add_u64 v[216:217], s[28:29], 0, v[162:163]
	s_addc_u32 s81, s29, 0
	s_add_i32 s51, s77, s9
	global_load_lds_dwordx4 v[216:217], off
	v_lshl_add_u64 v[218:219], s[80:81], 0, v[166:167]
	s_mov_b32 m0, s51
	v_lshl_add_u64 v[220:221], s[30:31], 0, v[164:165]
	global_load_lds_dwordx4 v[218:219], off
	v_lshl_add_u64 v[218:219], s[80:81], 0, v[162:163]
	s_add_i32 m0, s51, 0x2000
	s_nop 0
	global_load_lds_dwordx4 v[218:219], off
	v_lshl_add_u64 v[218:219], s[30:31], 0, v[168:169]
	s_mov_b32 m0, s14
	s_nop 0
	global_load_lds_dwordx4 v[218:219], off
	s_mov_b32 m0, s15
	s_nop 0
	global_load_lds_dwordx4 v[220:221], off
	s_waitcnt vmcnt(8)
	s_waitcnt lgkmcnt(0)
	s_barrier
	v_mfma_f32_16x16x32_bf16 v[62:65], v[130:133], v[174:177], v[62:65]
	v_mfma_f32_16x16x32_bf16 v[58:61], v[138:141], v[174:177], v[58:61]
	v_mfma_f32_16x16x32_bf16 v[46:49], v[130:133], v[184:187], v[46:49]
	v_mfma_f32_16x16x32_bf16 v[42:45], v[138:141], v[184:187], v[42:45]
	v_mfma_f32_16x16x32_bf16 v[30:33], v[130:133], v[200:203], v[30:33]
	v_mfma_f32_16x16x32_bf16 v[26:29], v[138:141], v[200:203], v[26:29]
	v_mfma_f32_16x16x32_bf16 v[14:17], v[130:133], v[208:211], v[14:17]
	v_mfma_f32_16x16x32_bf16 v[10:13], v[138:141], v[208:211], v[10:13]
	v_mfma_f32_16x16x32_bf16 v[62:65], v[134:137], v[180:183], v[62:65]
	v_mfma_f32_16x16x32_bf16 v[58:61], v[142:145], v[180:183], v[58:61]
	v_mfma_f32_16x16x32_bf16 v[46:49], v[134:137], v[188:191], v[46:49]
	v_mfma_f32_16x16x32_bf16 v[42:45], v[142:145], v[188:191], v[42:45]
	v_mfma_f32_16x16x32_bf16 v[30:33], v[134:137], v[204:207], v[30:33]
	v_mfma_f32_16x16x32_bf16 v[26:29], v[142:145], v[204:207], v[26:29]
	v_mfma_f32_16x16x32_bf16 v[14:17], v[134:137], v[212:215], v[14:17]
	v_mfma_f32_16x16x32_bf16 v[10:13], v[142:145], v[212:215], v[10:13]
	v_mfma_f32_16x16x32_bf16 v[54:57], v[146:149], v[174:177], v[54:57]
	v_mfma_f32_16x16x32_bf16 v[50:53], v[154:157], v[174:177], v[50:53]
	v_mfma_f32_16x16x32_bf16 v[38:41], v[146:149], v[184:187], v[38:41]
	v_mfma_f32_16x16x32_bf16 v[34:37], v[154:157], v[184:187], v[34:37]
	v_mfma_f32_16x16x32_bf16 v[22:25], v[146:149], v[200:203], v[22:25]
	v_mfma_f32_16x16x32_bf16 v[18:21], v[154:157], v[200:203], v[18:21]
	v_mfma_f32_16x16x32_bf16 v[6:9], v[146:149], v[208:211], v[6:9]
	v_mfma_f32_16x16x32_bf16 v[2:5], v[154:157], v[208:211], v[2:5]
	v_mfma_f32_16x16x32_bf16 v[54:57], v[150:153], v[180:183], v[54:57]
	v_mfma_f32_16x16x32_bf16 v[50:53], v[158:161], v[180:183], v[50:53]
	v_mfma_f32_16x16x32_bf16 v[38:41], v[150:153], v[188:191], v[38:41]
	v_mfma_f32_16x16x32_bf16 v[34:37], v[158:161], v[188:191], v[34:37]
	v_mfma_f32_16x16x32_bf16 v[22:25], v[150:153], v[204:207], v[22:25]
	v_mfma_f32_16x16x32_bf16 v[18:21], v[158:161], v[204:207], v[18:21]
	v_mfma_f32_16x16x32_bf16 v[6:9], v[150:153], v[212:215], v[6:9]
	v_mfma_f32_16x16x32_bf16 v[2:5], v[158:161], v[212:215], v[2:5]
	s_barrier
	s_add_i32 s51, 0, 0x18000
	v_add_u32_e32 v0, s51, v179
	s_add_i32 s77, 0, 0x1c000
	ds_read_b128 v[130:133], v0
	ds_read_b128 v[134:137], v0 offset:1024
	ds_read_b128 v[138:141], v0 offset:2048
	ds_read_b128 v[142:145], v0 offset:3072
	v_add_u32_e32 v0, s77, v179
	ds_read_b128 v[146:149], v0
	ds_read_b128 v[150:153], v0 offset:1024
	ds_read_b128 v[154:157], v0 offset:2048
	ds_read_b128 v[158:161], v0 offset:3072
	s_add_u32 s30, s30, 0x100000
	s_addc_u32 s31, s31, 0
	s_mov_b32 m0, s52
	v_lshl_add_u64 v[222:223], s[30:31], 0, v[168:169]
	ds_read_b128 v[174:177], v192 offset:32768
	ds_read_b128 v[180:183], v192 offset:33792
	ds_read_b128 v[184:187], v192 offset:34816
	ds_read_b128 v[188:191], v192 offset:35840
	ds_read_b128 v[200:203], v192 offset:36864
	ds_read_b128 v[204:207], v192 offset:37888
	ds_read_b128 v[208:211], v192 offset:38912
	ds_read_b128 v[212:215], v192 offset:39936
	global_load_lds_dwordx4 v[222:223], off
	v_lshl_add_u64 v[222:223], s[30:31], 0, v[164:165]
	s_mov_b32 m0, s53
	s_nop 0
	global_load_lds_dwordx4 v[222:223], off
	s_waitcnt vmcnt(8)
	s_waitcnt lgkmcnt(0)
	s_barrier
	v_mfma_f32_16x16x32_bf16 v[126:129], v[130:133], v[174:177], v[126:129]
	v_mfma_f32_16x16x32_bf16 v[122:125], v[138:141], v[174:177], v[122:125]
	v_mfma_f32_16x16x32_bf16 v[110:113], v[130:133], v[184:187], v[110:113]
	v_mfma_f32_16x16x32_bf16 v[106:109], v[138:141], v[184:187], v[106:109]
	v_mfma_f32_16x16x32_bf16 v[94:97], v[130:133], v[200:203], v[94:97]
	v_mfma_f32_16x16x32_bf16 v[90:93], v[138:141], v[200:203], v[90:93]
	v_mfma_f32_16x16x32_bf16 v[78:81], v[130:133], v[208:211], v[78:81]
	v_mfma_f32_16x16x32_bf16 v[74:77], v[138:141], v[208:211], v[74:77]
	v_mfma_f32_16x16x32_bf16 v[126:129], v[134:137], v[180:183], v[126:129]
	v_mfma_f32_16x16x32_bf16 v[122:125], v[142:145], v[180:183], v[122:125]
	v_mfma_f32_16x16x32_bf16 v[110:113], v[134:137], v[188:191], v[110:113]
	v_mfma_f32_16x16x32_bf16 v[106:109], v[142:145], v[188:191], v[106:109]
	v_mfma_f32_16x16x32_bf16 v[94:97], v[134:137], v[204:207], v[94:97]
	v_mfma_f32_16x16x32_bf16 v[90:93], v[142:145], v[204:207], v[90:93]
	v_mfma_f32_16x16x32_bf16 v[78:81], v[134:137], v[212:215], v[78:81]
	v_mfma_f32_16x16x32_bf16 v[74:77], v[142:145], v[212:215], v[74:77]
	v_mfma_f32_16x16x32_bf16 v[118:121], v[146:149], v[174:177], v[118:121]
	v_mfma_f32_16x16x32_bf16 v[114:117], v[154:157], v[174:177], v[114:117]
	v_mfma_f32_16x16x32_bf16 v[102:105], v[146:149], v[184:187], v[102:105]
	v_mfma_f32_16x16x32_bf16 v[98:101], v[154:157], v[184:187], v[98:101]
	v_mfma_f32_16x16x32_bf16 v[86:89], v[146:149], v[200:203], v[86:89]
	v_mfma_f32_16x16x32_bf16 v[82:85], v[154:157], v[200:203], v[82:85]
	v_mfma_f32_16x16x32_bf16 v[70:73], v[146:149], v[208:211], v[70:73]
	v_mfma_f32_16x16x32_bf16 v[66:69], v[154:157], v[208:211], v[66:69]
	v_mfma_f32_16x16x32_bf16 v[118:121], v[150:153], v[180:183], v[118:121]
	v_mfma_f32_16x16x32_bf16 v[114:117], v[158:161], v[180:183], v[114:117]
	v_mfma_f32_16x16x32_bf16 v[102:105], v[150:153], v[188:191], v[102:105]
	v_mfma_f32_16x16x32_bf16 v[98:101], v[158:161], v[188:191], v[98:101]
	v_mfma_f32_16x16x32_bf16 v[86:89], v[150:153], v[204:207], v[86:89]
	v_mfma_f32_16x16x32_bf16 v[82:85], v[158:161], v[204:207], v[82:85]
	v_mfma_f32_16x16x32_bf16 v[70:73], v[150:153], v[212:215], v[70:73]
	v_mfma_f32_16x16x32_bf16 v[66:69], v[158:161], v[212:215], v[66:69]
	s_barrier
	s_add_i32 s30, s51, s9
	v_lshl_add_u64 v[194:195], v[194:195], 0, s[12:13]
	s_mov_b32 m0, s30
	ds_read_b128 v[174:177], v192 offset:49152
	ds_read_b128 v[180:183], v192 offset:50176
	ds_read_b128 v[184:187], v192 offset:51200
	ds_read_b128 v[188:191], v192 offset:52224
	ds_read_b128 v[200:203], v192 offset:53248
	ds_read_b128 v[204:207], v192 offset:54272
	ds_read_b128 v[208:211], v192 offset:55296
	ds_read_b128 v[212:215], v192 offset:56320
	global_load_lds_dwordx4 v[194:195], off
	s_add_i32 m0, s30, 0x2000
	s_add_u32 s28, s28, 0x100080
	v_lshl_add_u64 v[194:195], v[216:217], 0, s[12:13]
	s_addc_u32 s29, s29, 0
	s_add_i32 s30, s77, s9
	global_load_lds_dwordx4 v[194:195], off
	v_lshl_add_u64 v[194:195], s[28:29], 0, v[166:167]
	s_mov_b32 m0, s30
	s_nop 0
	global_load_lds_dwordx4 v[194:195], off
	v_lshl_add_u64 v[194:195], s[28:29], 0, v[162:163]
	s_add_i32 m0, s30, 0x2000
	s_nop 0
	global_load_lds_dwordx4 v[194:195], off
	v_lshl_add_u64 v[194:195], v[218:219], 0, s[12:13]
	s_mov_b32 m0, s54
	s_nop 0
	global_load_lds_dwordx4 v[194:195], off
	v_lshl_add_u64 v[194:195], v[220:221], 0, s[12:13]
	s_mov_b32 m0, s55
	s_nop 0
	global_load_lds_dwordx4 v[194:195], off
	s_waitcnt vmcnt(8)
	s_waitcnt lgkmcnt(0)
	s_barrier
	v_mfma_f32_16x16x32_bf16 v[62:65], v[130:133], v[174:177], v[62:65]
	v_mfma_f32_16x16x32_bf16 v[58:61], v[138:141], v[174:177], v[58:61]
	v_mfma_f32_16x16x32_bf16 v[46:49], v[130:133], v[184:187], v[46:49]
	v_mfma_f32_16x16x32_bf16 v[42:45], v[138:141], v[184:187], v[42:45]
	v_mfma_f32_16x16x32_bf16 v[30:33], v[130:133], v[200:203], v[30:33]
	v_mfma_f32_16x16x32_bf16 v[26:29], v[138:141], v[200:203], v[26:29]
	v_mfma_f32_16x16x32_bf16 v[14:17], v[130:133], v[208:211], v[14:17]
	v_mfma_f32_16x16x32_bf16 v[10:13], v[138:141], v[208:211], v[10:13]
	v_mfma_f32_16x16x32_bf16 v[62:65], v[134:137], v[180:183], v[62:65]
	v_mfma_f32_16x16x32_bf16 v[58:61], v[142:145], v[180:183], v[58:61]
	v_mfma_f32_16x16x32_bf16 v[46:49], v[134:137], v[188:191], v[46:49]
	v_mfma_f32_16x16x32_bf16 v[42:45], v[142:145], v[188:191], v[42:45]
	v_mfma_f32_16x16x32_bf16 v[30:33], v[134:137], v[204:207], v[30:33]
	v_mfma_f32_16x16x32_bf16 v[26:29], v[142:145], v[204:207], v[26:29]
	v_mfma_f32_16x16x32_bf16 v[14:17], v[134:137], v[212:215], v[14:17]
	v_mfma_f32_16x16x32_bf16 v[10:13], v[142:145], v[212:215], v[10:13]
	v_mfma_f32_16x16x32_bf16 v[54:57], v[146:149], v[174:177], v[54:57]
	v_mfma_f32_16x16x32_bf16 v[50:53], v[154:157], v[174:177], v[50:53]
	v_mfma_f32_16x16x32_bf16 v[38:41], v[146:149], v[184:187], v[38:41]
	v_mfma_f32_16x16x32_bf16 v[34:37], v[154:157], v[184:187], v[34:37]
	v_mfma_f32_16x16x32_bf16 v[22:25], v[146:149], v[200:203], v[22:25]
	v_mfma_f32_16x16x32_bf16 v[18:21], v[154:157], v[200:203], v[18:21]
	v_mfma_f32_16x16x32_bf16 v[6:9], v[146:149], v[208:211], v[6:9]
	v_mfma_f32_16x16x32_bf16 v[2:5], v[154:157], v[208:211], v[2:5]
	v_mfma_f32_16x16x32_bf16 v[54:57], v[150:153], v[180:183], v[54:57]
	v_mfma_f32_16x16x32_bf16 v[50:53], v[158:161], v[180:183], v[50:53]
	v_mfma_f32_16x16x32_bf16 v[38:41], v[150:153], v[188:191], v[38:41]
	v_mfma_f32_16x16x32_bf16 v[34:37], v[158:161], v[188:191], v[34:37]
	v_mfma_f32_16x16x32_bf16 v[22:25], v[150:153], v[204:207], v[22:25]
	v_mfma_f32_16x16x32_bf16 v[18:21], v[158:161], v[204:207], v[18:21]
	v_mfma_f32_16x16x32_bf16 v[6:9], v[150:153], v[212:215], v[6:9]
	v_mfma_f32_16x16x32_bf16 v[2:5], v[158:161], v[212:215], v[2:5]
	s_barrier
	s_add_i32 s50, s50, 2
	s_add_u32 s0, s0, 0x100
	s_addc_u32 s1, s1, 0
	s_add_u32 s41, s41, 0x100
	s_addc_u32 s43, s43, 0
	s_cmp_gt_u32 s50, 61
	s_cbranch_scc0 .LBB0_230
	s_and_b64 vcc, exec, s[22:23]
	s_cbranch_vccz .LBB0_233
	s_barrier

.LBB0_300:
	s_add_u32 s100, s0, 0xfff80000
	s_addc_u32 s101, s1, -1
	s_add_u32 s28, s0, 0xfff80080
	s_addc_u32 s29, s1, -1
	s_add_i32 s42, 0, 0x10000
	s_cmp_eq_u32 s41, 28
	s_cselect_b32 s31, s18, s29
	s_cselect_b32 s30, s19, s28
	v_add_u32_e32 v0, s42, v199
	s_cselect_b32 s29, s27, s40
	s_cselect_b32 s28, s34, s35
	s_add_i32 s49, 0, 0x14000
	ds_read_b128 v[2:5], v0
	ds_read_b128 v[6:9], v0 offset:1024
	ds_read_b128 v[10:13], v0 offset:2048
	ds_read_b128 v[14:17], v0 offset:3072
	v_add_u32_e32 v0, s49, v199
	ds_read_b128 v[146:149], v0
	ds_read_b128 v[150:153], v0 offset:1024
	ds_read_b128 v[154:157], v0 offset:2048
	ds_read_b128 v[158:161], v0 offset:3072
	v_lshl_add_u64 v[194:195], s[100:101], 0, v[162:163]
	s_mov_b32 m0, s15
	ds_read_b128 v[174:177], v250
	ds_read_b128 v[178:181], v250 offset:1024
	ds_read_b128 v[182:185], v250 offset:2048
	ds_read_b128 v[186:189], v250 offset:3072
	ds_read_b128 v[190:193], v250 offset:4096
	ds_read_b128 v[200:203], v250 offset:5120
	ds_read_b128 v[204:207], v250 offset:6144
	ds_read_b128 v[208:211], v250 offset:7168
	global_load_lds_dwordx4 v[194:195], off
	v_lshl_add_u64 v[194:195], s[100:101], 0, v[166:167]
	s_mov_b32 m0, s88
	s_nop 0
	global_load_lds_dwordx4 v[194:195], off
	v_lshl_add_u64 v[194:195], s[0:1], 0, v[170:171]
	s_add_i32 m0, s21, 0xc000
	s_nop 0
	global_load_lds_dwordx4 v[194:195], off
	v_lshl_add_u64 v[194:195], s[0:1], 0, v[172:173]
	s_add_i32 m0, s21, 0xe000
	s_nop 0
	global_load_lds_dwordx4 v[194:195], off
	s_waitcnt vmcnt(8)
	s_waitcnt lgkmcnt(0)
	s_barrier
	v_mfma_i32_16x16x64_i8 v[142:145], v[2:5], v[174:177], v[142:145]
	v_mfma_i32_16x16x64_i8 v[138:141], v[10:13], v[174:177], v[138:141]
	v_mfma_i32_16x16x64_i8 v[134:137], v[2:5], v[182:185], v[134:137]
	v_mfma_i32_16x16x64_i8 v[130:133], v[10:13], v[182:185], v[130:133]
	v_mfma_i32_16x16x64_i8 v[122:125], v[2:5], v[190:193], v[122:125]
	v_mfma_i32_16x16x64_i8 v[114:117], v[10:13], v[190:193], v[114:117]
	v_mfma_i32_16x16x64_i8 v[106:109], v[2:5], v[204:207], v[106:109]
	v_mfma_i32_16x16x64_i8 v[98:101], v[10:13], v[204:207], v[98:101]
	v_mfma_i32_16x16x64_i8 v[142:145], v[6:9], v[178:181], v[142:145]
	v_mfma_i32_16x16x64_i8 v[138:141], v[14:17], v[178:181], v[138:141]
	v_mfma_i32_16x16x64_i8 v[134:137], v[6:9], v[186:189], v[134:137]
	v_mfma_i32_16x16x64_i8 v[130:133], v[14:17], v[186:189], v[130:133]
	v_mfma_i32_16x16x64_i8 v[122:125], v[6:9], v[200:203], v[122:125]
	v_mfma_i32_16x16x64_i8 v[114:117], v[14:17], v[200:203], v[114:117]
	v_mfma_i32_16x16x64_i8 v[106:109], v[6:9], v[208:211], v[106:109]
	v_mfma_i32_16x16x64_i8 v[98:101], v[14:17], v[208:211], v[98:101]
	v_mfma_i32_16x16x64_i8 v[126:129], v[146:149], v[174:177], v[126:129]
	v_mfma_i32_16x16x64_i8 v[118:121], v[154:157], v[174:177], v[118:121]
	v_mfma_i32_16x16x64_i8 v[110:113], v[146:149], v[182:185], v[110:113]
	v_mfma_i32_16x16x64_i8 v[102:105], v[154:157], v[182:185], v[102:105]
	v_mfma_i32_16x16x64_i8 v[94:97], v[146:149], v[190:193], v[94:97]
	v_mfma_i32_16x16x64_i8 v[90:93], v[154:157], v[190:193], v[90:93]
	v_mfma_i32_16x16x64_i8 v[86:89], v[146:149], v[204:207], v[86:89]
	v_mfma_i32_16x16x64_i8 v[82:85], v[154:157], v[204:207], v[82:85]
	v_mfma_i32_16x16x64_i8 v[126:129], v[150:153], v[178:181], v[126:129]
	v_mfma_i32_16x16x64_i8 v[118:121], v[158:161], v[178:181], v[118:121]
	v_mfma_i32_16x16x64_i8 v[110:113], v[150:153], v[186:189], v[110:113]
	v_mfma_i32_16x16x64_i8 v[102:105], v[158:161], v[186:189], v[102:105]
	v_mfma_i32_16x16x64_i8 v[94:97], v[150:153], v[200:203], v[94:97]
	v_mfma_i32_16x16x64_i8 v[90:93], v[158:161], v[200:203], v[90:93]
	v_mfma_i32_16x16x64_i8 v[86:89], v[150:153], v[208:211], v[86:89]
	v_mfma_i32_16x16x64_i8 v[82:85], v[158:161], v[208:211], v[82:85]
	s_barrier
	s_add_i32 s42, s42, s81
	v_lshl_add_u64 v[194:195], s[28:29], 0, v[164:165]
	s_mov_b32 m0, s42
	ds_read_b128 v[174:177], v250 offset:16384
	ds_read_b128 v[178:181], v250 offset:17408
	ds_read_b128 v[182:185], v250 offset:18432
	ds_read_b128 v[186:189], v250 offset:19456
	ds_read_b128 v[190:193], v250 offset:20480
	ds_read_b128 v[200:203], v250 offset:21504
	ds_read_b128 v[204:207], v250 offset:22528
	ds_read_b128 v[208:211], v250 offset:23552
	global_load_lds_dwordx4 v[194:195], off
	s_add_i32 m0, s42, 0x2000
	s_add_u32 s42, s28, 0x80000
	v_lshl_add_u64 v[212:213], s[28:29], 0, v[168:169]
	s_addc_u32 s43, s29, 0
	s_add_i32 s49, s49, s81
	global_load_lds_dwordx4 v[212:213], off
	v_lshl_add_u64 v[214:215], s[42:43], 0, v[164:165]
	s_mov_b32 m0, s49
	v_lshl_add_u64 v[216:217], s[30:31], 0, v[166:167]
	global_load_lds_dwordx4 v[214:215], off
	v_lshl_add_u64 v[214:215], s[42:43], 0, v[168:169]
	s_add_i32 m0, s49, 0x2000
	s_nop 0
	global_load_lds_dwordx4 v[214:215], off
	v_lshl_add_u64 v[214:215], s[30:31], 0, v[162:163]
	s_waitcnt vmcnt(6)
	s_waitcnt lgkmcnt(0)
	s_barrier
	v_mfma_i32_16x16x64_i8 v[78:81], v[2:5], v[174:177], v[78:81]
	v_mfma_i32_16x16x64_i8 v[74:77], v[10:13], v[174:177], v[74:77]
	v_mfma_i32_16x16x64_i8 v[70:73], v[2:5], v[182:185], v[70:73]
	v_mfma_i32_16x16x64_i8 v[66:69], v[10:13], v[182:185], v[66:69]
	v_mfma_i32_16x16x64_i8 v[54:57], v[2:5], v[190:193], v[54:57]
	v_mfma_i32_16x16x64_i8 v[50:53], v[10:13], v[190:193], v[50:53]
	v_mfma_i32_16x16x64_i8 v[2:5], v[2:5], v[204:207], v[38:41]
	v_mfma_i32_16x16x64_i8 v[78:81], v[6:9], v[178:181], v[78:81]
	v_mfma_i32_16x16x64_i8 v[74:77], v[14:17], v[178:181], v[74:77]
	v_mfma_i32_16x16x64_i8 v[70:73], v[6:9], v[186:189], v[70:73]
	v_mfma_i32_16x16x64_i8 v[66:69], v[14:17], v[186:189], v[66:69]
	v_mfma_i32_16x16x64_i8 v[54:57], v[6:9], v[200:203], v[54:57]
	v_mfma_i32_16x16x64_i8 v[50:53], v[14:17], v[200:203], v[50:53]
	v_mfma_i32_16x16x64_i8 v[2:5], v[6:9], v[208:211], v[2:5]
	v_mfma_i32_16x16x64_i8 v[6:9], v[10:13], v[204:207], v[34:37]
	v_mfma_i32_16x16x64_i8 v[6:9], v[14:17], v[208:211], v[6:9]
	v_mfma_i32_16x16x64_i8 v[34:37], v[146:149], v[182:185], v[46:49]
	v_mfma_i32_16x16x64_i8 v[46:49], v[150:153], v[186:189], v[34:37]
	v_mfma_i32_16x16x64_i8 v[34:37], v[154:157], v[182:185], v[42:45]
	v_mfma_i32_16x16x64_i8 v[30:33], v[146:149], v[190:193], v[30:33]
	v_mfma_i32_16x16x64_i8 v[26:29], v[154:157], v[190:193], v[26:29]
	v_mfma_i32_16x16x64_i8 v[22:25], v[146:149], v[204:207], v[22:25]
	v_mfma_i32_16x16x64_i8 v[18:21], v[154:157], v[204:207], v[18:21]
	v_mfma_i32_16x16x64_i8 v[10:13], v[146:149], v[174:177], v[62:65]
	v_mfma_i32_16x16x64_i8 v[14:17], v[154:157], v[174:177], v[58:61]
	v_mfma_i32_16x16x64_i8 v[42:45], v[158:161], v[186:189], v[34:37]
	v_mfma_i32_16x16x64_i8 v[30:33], v[150:153], v[200:203], v[30:33]
	v_mfma_i32_16x16x64_i8 v[26:29], v[158:161], v[200:203], v[26:29]
	v_mfma_i32_16x16x64_i8 v[22:25], v[150:153], v[208:211], v[22:25]
	v_mfma_i32_16x16x64_i8 v[18:21], v[158:161], v[208:211], v[18:21]
	v_mfma_i32_16x16x64_i8 v[10:13], v[150:153], v[178:181], v[10:13]
	v_mfma_i32_16x16x64_i8 v[14:17], v[158:161], v[178:181], v[14:17]
	s_barrier
	s_add_i32 s42, 0, 0x18000
	v_add_u32_e32 v0, s42, v199
	s_add_i32 s43, 0, 0x1c000
	ds_read_b128 v[34:37], v0
	ds_read_b128 v[38:41], v0 offset:1024
	ds_read_b128 v[58:61], v0 offset:2048
	ds_read_b128 v[62:65], v0 offset:3072
	v_add_u32_e32 v0, s43, v199
	ds_read_b128 v[146:149], v0
	ds_read_b128 v[150:153], v0 offset:1024
	ds_read_b128 v[154:157], v0 offset:2048
	ds_read_b128 v[158:161], v0 offset:3072
	s_add_u32 s30, s30, 0x80000
	s_addc_u32 s31, s31, 0
	s_mov_b32 m0, s21
	v_lshl_add_u64 v[218:219], s[30:31], 0, v[162:163]
	ds_read_b128 v[174:177], v250 offset:32768
	ds_read_b128 v[178:181], v250 offset:33792
	ds_read_b128 v[182:185], v250 offset:34816
	ds_read_b128 v[186:189], v250 offset:35840
	ds_read_b128 v[190:193], v250 offset:36864
	ds_read_b128 v[200:203], v250 offset:37888
	ds_read_b128 v[204:207], v250 offset:38912
	ds_read_b128 v[208:211], v250 offset:39936
	global_load_lds_dwordx4 v[214:215], off
	s_mov_b32 m0, s57
	s_nop 0
	global_load_lds_dwordx4 v[216:217], off
	s_mov_b32 m0, s73
	s_nop 0
	global_load_lds_dwordx4 v[218:219], off
	v_lshl_add_u64 v[218:219], s[30:31], 0, v[166:167]
	s_mov_b32 m0, s76
	s_nop 0
	global_load_lds_dwordx4 v[218:219], off
	s_waitcnt vmcnt(8)
	s_waitcnt lgkmcnt(0)
	s_barrier
	v_mfma_i32_16x16x64_i8 v[142:145], v[34:37], v[174:177], v[142:145]
	v_mfma_i32_16x16x64_i8 v[138:141], v[58:61], v[174:177], v[138:141]
	v_mfma_i32_16x16x64_i8 v[134:137], v[34:37], v[182:185], v[134:137]
	v_mfma_i32_16x16x64_i8 v[130:133], v[58:61], v[182:185], v[130:133]
	v_mfma_i32_16x16x64_i8 v[122:125], v[34:37], v[190:193], v[122:125]
	v_mfma_i32_16x16x64_i8 v[114:117], v[58:61], v[190:193], v[114:117]
	v_mfma_i32_16x16x64_i8 v[106:109], v[34:37], v[204:207], v[106:109]
	v_mfma_i32_16x16x64_i8 v[98:101], v[58:61], v[204:207], v[98:101]
	v_mfma_i32_16x16x64_i8 v[142:145], v[38:41], v[178:181], v[142:145]
	v_mfma_i32_16x16x64_i8 v[138:141], v[62:65], v[178:181], v[138:141]
	v_mfma_i32_16x16x64_i8 v[134:137], v[38:41], v[186:189], v[134:137]
	v_mfma_i32_16x16x64_i8 v[130:133], v[62:65], v[186:189], v[130:133]
	v_mfma_i32_16x16x64_i8 v[122:125], v[38:41], v[200:203], v[122:125]
	v_mfma_i32_16x16x64_i8 v[114:117], v[62:65], v[200:203], v[114:117]
	v_mfma_i32_16x16x64_i8 v[106:109], v[38:41], v[208:211], v[106:109]
	v_mfma_i32_16x16x64_i8 v[98:101], v[62:65], v[208:211], v[98:101]
	v_mfma_i32_16x16x64_i8 v[126:129], v[146:149], v[174:177], v[126:129]
	v_mfma_i32_16x16x64_i8 v[118:121], v[154:157], v[174:177], v[118:121]
	v_mfma_i32_16x16x64_i8 v[110:113], v[146:149], v[182:185], v[110:113]
	v_mfma_i32_16x16x64_i8 v[102:105], v[154:157], v[182:185], v[102:105]
	v_mfma_i32_16x16x64_i8 v[94:97], v[146:149], v[190:193], v[94:97]
	v_mfma_i32_16x16x64_i8 v[90:93], v[154:157], v[190:193], v[90:93]
	v_mfma_i32_16x16x64_i8 v[86:89], v[146:149], v[204:207], v[86:89]
	v_mfma_i32_16x16x64_i8 v[82:85], v[154:157], v[204:207], v[82:85]
	v_mfma_i32_16x16x64_i8 v[126:129], v[150:153], v[178:181], v[126:129]
	v_mfma_i32_16x16x64_i8 v[118:121], v[158:161], v[178:181], v[118:121]
	v_mfma_i32_16x16x64_i8 v[110:113], v[150:153], v[186:189], v[110:113]
	v_mfma_i32_16x16x64_i8 v[102:105], v[158:161], v[186:189], v[102:105]
	v_mfma_i32_16x16x64_i8 v[94:97], v[150:153], v[200:203], v[94:97]
	v_mfma_i32_16x16x64_i8 v[90:93], v[158:161], v[200:203], v[90:93]
	v_mfma_i32_16x16x64_i8 v[86:89], v[150:153], v[208:211], v[86:89]
	v_mfma_i32_16x16x64_i8 v[82:85], v[158:161], v[208:211], v[82:85]
	s_barrier
	s_add_i32 s30, s42, s81
	v_lshl_add_u64 v[194:195], v[194:195], 0, s[12:13]
	s_mov_b32 m0, s30
	ds_read_b128 v[174:177], v250 offset:49152
	ds_read_b128 v[178:181], v250 offset:50176
	ds_read_b128 v[182:185], v250 offset:51200
	ds_read_b128 v[186:189], v250 offset:52224
	ds_read_b128 v[190:193], v250 offset:53248
	ds_read_b128 v[200:203], v250 offset:54272
	ds_read_b128 v[204:207], v250 offset:55296
	ds_read_b128 v[208:211], v250 offset:56320
	global_load_lds_dwordx4 v[194:195], off
	s_add_i32 m0, s30, 0x2000
	s_add_u32 s28, s28, 0x80080
	v_lshl_add_u64 v[194:195], v[212:213], 0, s[12:13]
	s_addc_u32 s29, s29, 0
	s_add_i32 s30, s43, s81
	global_load_lds_dwordx4 v[194:195], off
	v_lshl_add_u64 v[194:195], s[28:29], 0, v[164:165]
	s_mov_b32 m0, s30
	s_nop 0
	global_load_lds_dwordx4 v[194:195], off
	v_lshl_add_u64 v[194:195], s[28:29], 0, v[168:169]
	s_add_i32 m0, s30, 0x2000
	s_nop 0
	global_load_lds_dwordx4 v[194:195], off
	s_waitcnt vmcnt(6)
	s_waitcnt lgkmcnt(0)
	s_barrier
	v_mfma_i32_16x16x64_i8 v[78:81], v[34:37], v[174:177], v[78:81]
	v_mfma_i32_16x16x64_i8 v[70:73], v[34:37], v[182:185], v[70:73]
	v_mfma_i32_16x16x64_i8 v[54:57], v[34:37], v[190:193], v[54:57]
	v_mfma_i32_16x16x64_i8 v[2:5], v[34:37], v[204:207], v[2:5]
	v_mfma_i32_16x16x64_i8 v[78:81], v[38:41], v[178:181], v[78:81]
	v_mfma_i32_16x16x64_i8 v[74:77], v[58:61], v[174:177], v[74:77]
	v_mfma_i32_16x16x64_i8 v[70:73], v[38:41], v[186:189], v[70:73]
	v_mfma_i32_16x16x64_i8 v[66:69], v[58:61], v[182:185], v[66:69]
	v_mfma_i32_16x16x64_i8 v[54:57], v[38:41], v[200:203], v[54:57]
	v_mfma_i32_16x16x64_i8 v[50:53], v[58:61], v[190:193], v[50:53]
	v_mfma_i32_16x16x64_i8 v[38:41], v[38:41], v[208:211], v[2:5]
	v_mfma_i32_16x16x64_i8 v[2:5], v[58:61], v[204:207], v[6:9]
	v_mfma_i32_16x16x64_i8 v[74:77], v[62:65], v[178:181], v[74:77]
	v_mfma_i32_16x16x64_i8 v[66:69], v[62:65], v[186:189], v[66:69]
	v_mfma_i32_16x16x64_i8 v[50:53], v[62:65], v[200:203], v[50:53]
	v_mfma_i32_16x16x64_i8 v[34:37], v[62:65], v[208:211], v[2:5]
	v_mfma_i32_16x16x64_i8 v[2:5], v[146:149], v[174:177], v[10:13]
	v_mfma_i32_16x16x64_i8 v[62:65], v[150:153], v[178:181], v[2:5]
	v_mfma_i32_16x16x64_i8 v[2:5], v[154:157], v[174:177], v[14:17]
	v_mfma_i32_16x16x64_i8 v[58:61], v[158:161], v[178:181], v[2:5]
	v_mfma_i32_16x16x64_i8 v[2:5], v[146:149], v[182:185], v[46:49]
	v_mfma_i32_16x16x64_i8 v[46:49], v[150:153], v[186:189], v[2:5]
	v_mfma_i32_16x16x64_i8 v[2:5], v[154:157], v[182:185], v[42:45]
	v_mfma_i32_16x16x64_i8 v[42:45], v[158:161], v[186:189], v[2:5]
	v_mfma_i32_16x16x64_i8 v[2:5], v[146:149], v[190:193], v[30:33]
	v_mfma_i32_16x16x64_i8 v[30:33], v[150:153], v[200:203], v[2:5]
	v_mfma_i32_16x16x64_i8 v[2:5], v[154:157], v[190:193], v[26:29]
	v_mfma_i32_16x16x64_i8 v[26:29], v[158:161], v[200:203], v[2:5]
	v_mfma_i32_16x16x64_i8 v[2:5], v[146:149], v[204:207], v[22:25]
	v_mfma_i32_16x16x64_i8 v[22:25], v[150:153], v[208:211], v[2:5]
	v_mfma_i32_16x16x64_i8 v[2:5], v[154:157], v[204:207], v[18:21]
	v_mfma_i32_16x16x64_i8 v[18:21], v[158:161], v[208:211], v[2:5]
	s_barrier
	s_add_i32 s41, s41, 2
	s_add_u32 s0, s0, 0x100
	s_addc_u32 s1, s1, 0
	s_add_u32 s35, s35, 0x100
	s_addc_u32 s40, s40, 0
	s_cmp_gt_u32 s41, 29
	s_cbranch_scc0 .LBB0_300
	s_and_b64 vcc, exec, s[52:53]
	s_cbranch_vccz .LBB0_303
	s_barrier

.LBB0_577:
	s_add_u32 s34, s30, 0xfff80080
	s_addc_u32 s35, s31, -1
	s_add_i32 s66, 0, 0x10000
	s_cmp_eq_u32 s57, 28
	s_cselect_b32 s43, s19, s35
	s_cselect_b32 s42, s23, s34
	v_add_u32_e32 v0, s66, v228
	s_cselect_b32 s35, s25, s56
	s_cselect_b32 s34, s54, s55
	s_add_i32 s73, 0, 0x14000
	ds_read_b128 v[132:135], v0
	ds_read_b128 v[136:139], v0 offset:1024
	ds_read_b128 v[140:143], v0 offset:2048
	ds_read_b128 v[144:147], v0 offset:3072
	v_add_u32_e32 v0, s73, v228
	ds_read_b128 v[148:151], v0
	ds_read_b128 v[152:155], v0 offset:1024
	ds_read_b128 v[156:159], v0 offset:2048
	ds_read_b128 v[160:163], v0 offset:3072
	v_lshl_add_u64 v[2:3], s[30:31], 0, v[208:209]
	s_add_i32 m0, s46, 0xc000
	ds_read_b128 v[164:167], v230
	ds_read_b128 v[168:171], v230 offset:1024
	ds_read_b128 v[172:175], v230 offset:2048
	ds_read_b128 v[176:179], v230 offset:3072
	ds_read_b128 v[180:183], v230 offset:4096
	ds_read_b128 v[184:187], v230 offset:5120
	ds_read_b128 v[188:191], v230 offset:6144
	ds_read_b128 v[192:195], v230 offset:7168
	global_load_lds_dwordx4 v[2:3], off
	v_lshl_add_u64 v[2:3], s[30:31], 0, v[210:211]
	s_add_i32 m0, s46, 0xe000
	s_nop 0
	global_load_lds_dwordx4 v[2:3], off
	s_waitcnt vmcnt(8)
	s_waitcnt lgkmcnt(0)
	s_barrier
	v_mfma_f32_16x16x32_bf16 v[128:131], v[132:135], v[164:167], v[128:131]
	v_mfma_f32_16x16x32_bf16 v[124:127], v[140:143], v[164:167], v[124:127]
	v_mfma_f32_16x16x32_bf16 v[120:123], v[132:135], v[172:175], v[120:123]
	v_mfma_f32_16x16x32_bf16 v[116:119], v[140:143], v[172:175], v[116:119]
	v_mfma_f32_16x16x32_bf16 v[112:115], v[132:135], v[180:183], v[112:115]
	v_mfma_f32_16x16x32_bf16 v[108:111], v[140:143], v[180:183], v[108:111]
	v_mfma_f32_16x16x32_bf16 v[104:107], v[132:135], v[188:191], v[104:107]
	v_mfma_f32_16x16x32_bf16 v[100:103], v[140:143], v[188:191], v[100:103]
	v_mfma_f32_16x16x32_bf16 v[128:131], v[136:139], v[168:171], v[128:131]
	v_mfma_f32_16x16x32_bf16 v[124:127], v[144:147], v[168:171], v[124:127]
	v_mfma_f32_16x16x32_bf16 v[120:123], v[136:139], v[176:179], v[120:123]
	v_mfma_f32_16x16x32_bf16 v[116:119], v[144:147], v[176:179], v[116:119]
	v_mfma_f32_16x16x32_bf16 v[112:115], v[136:139], v[184:187], v[112:115]
	v_mfma_f32_16x16x32_bf16 v[108:111], v[144:147], v[184:187], v[108:111]
	v_mfma_f32_16x16x32_bf16 v[104:107], v[136:139], v[192:195], v[104:107]
	v_mfma_f32_16x16x32_bf16 v[100:103], v[144:147], v[192:195], v[100:103]
	v_mfma_f32_16x16x32_bf16 v[96:99], v[148:151], v[164:167], v[96:99]
	v_mfma_f32_16x16x32_bf16 v[92:95], v[156:159], v[164:167], v[92:95]
	v_mfma_f32_16x16x32_bf16 v[88:91], v[148:151], v[172:175], v[88:91]
	v_mfma_f32_16x16x32_bf16 v[84:87], v[156:159], v[172:175], v[84:87]
	v_mfma_f32_16x16x32_bf16 v[80:83], v[148:151], v[180:183], v[80:83]
	v_mfma_f32_16x16x32_bf16 v[76:79], v[156:159], v[180:183], v[76:79]
	v_mfma_f32_16x16x32_bf16 v[72:75], v[148:151], v[188:191], v[72:75]
	v_mfma_f32_16x16x32_bf16 v[68:71], v[156:159], v[188:191], v[68:71]
	v_mfma_f32_16x16x32_bf16 v[96:99], v[152:155], v[168:171], v[96:99]
	v_mfma_f32_16x16x32_bf16 v[92:95], v[160:163], v[168:171], v[92:95]
	v_mfma_f32_16x16x32_bf16 v[88:91], v[152:155], v[176:179], v[88:91]
	v_mfma_f32_16x16x32_bf16 v[84:87], v[160:163], v[176:179], v[84:87]
	v_mfma_f32_16x16x32_bf16 v[80:83], v[152:155], v[184:187], v[80:83]
	v_mfma_f32_16x16x32_bf16 v[76:79], v[160:163], v[184:187], v[76:79]
	v_mfma_f32_16x16x32_bf16 v[72:75], v[152:155], v[192:195], v[72:75]
	v_mfma_f32_16x16x32_bf16 v[68:71], v[160:163], v[192:195], v[68:71]
	s_barrier
	s_add_i32 s66, s66, s15
	v_lshl_add_u64 v[212:213], s[34:35], 0, v[204:205]
	s_mov_b32 m0, s66
	ds_read_b128 v[164:167], v230 offset:16384
	ds_read_b128 v[168:171], v230 offset:17408
	ds_read_b128 v[172:175], v230 offset:18432
	ds_read_b128 v[176:179], v230 offset:19456
	ds_read_b128 v[180:183], v230 offset:20480
	ds_read_b128 v[184:187], v230 offset:21504
	ds_read_b128 v[188:191], v230 offset:22528
	ds_read_b128 v[192:195], v230 offset:23552
	global_load_lds_dwordx4 v[212:213], off
	s_add_i32 m0, s66, 0x2000
	s_add_u32 s66, s34, 0x80000
	v_lshl_add_u64 v[214:215], s[34:35], 0, v[200:201]
	s_addc_u32 s67, s35, 0
	s_add_i32 s73, s73, s15
	global_load_lds_dwordx4 v[214:215], off
	v_lshl_add_u64 v[2:3], s[66:67], 0, v[204:205]
	s_mov_b32 m0, s73
	v_lshl_add_u64 v[216:217], s[42:43], 0, v[206:207]
	global_load_lds_dwordx4 v[2:3], off
	v_lshl_add_u64 v[2:3], s[66:67], 0, v[200:201]
	s_add_i32 m0, s73, 0x2000
	v_lshl_add_u64 v[218:219], s[42:43], 0, v[202:203]
	global_load_lds_dwordx4 v[2:3], off
	s_mov_b32 m0, s46
	s_nop 0
	global_load_lds_dwordx4 v[216:217], off
	s_mov_b32 m0, s47
	s_nop 0
	global_load_lds_dwordx4 v[218:219], off
	s_waitcnt vmcnt(8)
	s_waitcnt lgkmcnt(0)
	s_barrier
	v_mfma_f32_16x16x32_bf16 v[64:67], v[132:135], v[164:167], v[64:67]
	v_mfma_f32_16x16x32_bf16 v[60:63], v[140:143], v[164:167], v[60:63]
	v_mfma_f32_16x16x32_bf16 v[56:59], v[132:135], v[172:175], v[56:59]
	v_mfma_f32_16x16x32_bf16 v[52:55], v[140:143], v[172:175], v[52:55]
	v_mfma_f32_16x16x32_bf16 v[48:51], v[132:135], v[180:183], v[48:51]
	v_mfma_f32_16x16x32_bf16 v[44:47], v[140:143], v[180:183], v[44:47]
	v_mfma_f32_16x16x32_bf16 v[40:43], v[132:135], v[188:191], v[40:43]
	v_mfma_f32_16x16x32_bf16 v[36:39], v[140:143], v[188:191], v[36:39]
	v_mfma_f32_16x16x32_bf16 v[64:67], v[136:139], v[168:171], v[64:67]
	v_mfma_f32_16x16x32_bf16 v[60:63], v[144:147], v[168:171], v[60:63]
	v_mfma_f32_16x16x32_bf16 v[56:59], v[136:139], v[176:179], v[56:59]
	v_mfma_f32_16x16x32_bf16 v[52:55], v[144:147], v[176:179], v[52:55]
	v_mfma_f32_16x16x32_bf16 v[48:51], v[136:139], v[184:187], v[48:51]
	v_mfma_f32_16x16x32_bf16 v[44:47], v[144:147], v[184:187], v[44:47]
	v_mfma_f32_16x16x32_bf16 v[40:43], v[136:139], v[192:195], v[40:43]
	v_mfma_f32_16x16x32_bf16 v[36:39], v[144:147], v[192:195], v[36:39]
	v_mfma_f32_16x16x32_bf16 v[32:35], v[148:151], v[164:167], v[32:35]
	v_mfma_f32_16x16x32_bf16 v[28:31], v[156:159], v[164:167], v[28:31]
	v_mfma_f32_16x16x32_bf16 v[24:27], v[148:151], v[172:175], v[24:27]
	v_mfma_f32_16x16x32_bf16 v[20:23], v[156:159], v[172:175], v[20:23]
	v_mfma_f32_16x16x32_bf16 v[16:19], v[148:151], v[180:183], v[16:19]
	v_mfma_f32_16x16x32_bf16 v[12:15], v[156:159], v[180:183], v[12:15]
	v_mfma_f32_16x16x32_bf16 v[8:11], v[148:151], v[188:191], v[8:11]
	v_mfma_f32_16x16x32_bf16 v[2:5], v[156:159], v[188:191], v[4:7]
	v_mfma_f32_16x16x32_bf16 v[32:35], v[152:155], v[168:171], v[32:35]
	v_mfma_f32_16x16x32_bf16 v[28:31], v[160:163], v[168:171], v[28:31]
	v_mfma_f32_16x16x32_bf16 v[24:27], v[152:155], v[176:179], v[24:27]
	v_mfma_f32_16x16x32_bf16 v[20:23], v[160:163], v[176:179], v[20:23]
	v_mfma_f32_16x16x32_bf16 v[16:19], v[152:155], v[184:187], v[16:19]
	v_mfma_f32_16x16x32_bf16 v[12:15], v[160:163], v[184:187], v[12:15]
	v_mfma_f32_16x16x32_bf16 v[8:11], v[152:155], v[192:195], v[8:11]
	v_mfma_f32_16x16x32_bf16 v[2:5], v[160:163], v[192:195], v[2:5]
	s_barrier
	s_add_i32 s66, 0, 0x18000
	v_add_u32_e32 v0, s66, v228
	s_add_i32 s67, 0, 0x1c000
	ds_read_b128 v[132:135], v0
	ds_read_b128 v[136:139], v0 offset:1024
	ds_read_b128 v[140:143], v0 offset:2048
	ds_read_b128 v[144:147], v0 offset:3072
	v_add_u32_e32 v0, s67, v228
	ds_read_b128 v[148:151], v0
	ds_read_b128 v[152:155], v0 offset:1024
	ds_read_b128 v[156:159], v0 offset:2048
	ds_read_b128 v[160:163], v0 offset:3072
	s_add_u32 s42, s42, 0x80000
	s_addc_u32 s43, s43, 0
	s_mov_b32 m0, s48
	v_lshl_add_u64 v[6:7], s[42:43], 0, v[206:207]
	ds_read_b128 v[164:167], v230 offset:32768
	ds_read_b128 v[168:171], v230 offset:33792
	ds_read_b128 v[172:175], v230 offset:34816
	ds_read_b128 v[176:179], v230 offset:35840
	ds_read_b128 v[180:183], v230 offset:36864
	ds_read_b128 v[184:187], v230 offset:37888
	ds_read_b128 v[188:191], v230 offset:38912
	ds_read_b128 v[192:195], v230 offset:39936
	global_load_lds_dwordx4 v[6:7], off
	v_lshl_add_u64 v[6:7], s[42:43], 0, v[202:203]
	s_mov_b32 m0, s49
	s_nop 0
	global_load_lds_dwordx4 v[6:7], off
	s_waitcnt vmcnt(8)
	s_waitcnt lgkmcnt(0)
	s_barrier
	v_mfma_f32_16x16x32_bf16 v[128:131], v[132:135], v[164:167], v[128:131]
	v_mfma_f32_16x16x32_bf16 v[124:127], v[140:143], v[164:167], v[124:127]
	v_mfma_f32_16x16x32_bf16 v[120:123], v[132:135], v[172:175], v[120:123]
	v_mfma_f32_16x16x32_bf16 v[116:119], v[140:143], v[172:175], v[116:119]
	v_mfma_f32_16x16x32_bf16 v[112:115], v[132:135], v[180:183], v[112:115]
	v_mfma_f32_16x16x32_bf16 v[108:111], v[140:143], v[180:183], v[108:111]
	v_mfma_f32_16x16x32_bf16 v[104:107], v[132:135], v[188:191], v[104:107]
	v_mfma_f32_16x16x32_bf16 v[100:103], v[140:143], v[188:191], v[100:103]
	v_mfma_f32_16x16x32_bf16 v[128:131], v[136:139], v[168:171], v[128:131]
	v_mfma_f32_16x16x32_bf16 v[124:127], v[144:147], v[168:171], v[124:127]
	v_mfma_f32_16x16x32_bf16 v[120:123], v[136:139], v[176:179], v[120:123]
	v_mfma_f32_16x16x32_bf16 v[116:119], v[144:147], v[176:179], v[116:119]
	v_mfma_f32_16x16x32_bf16 v[112:115], v[136:139], v[184:187], v[112:115]
	v_mfma_f32_16x16x32_bf16 v[108:111], v[144:147], v[184:187], v[108:111]
	v_mfma_f32_16x16x32_bf16 v[104:107], v[136:139], v[192:195], v[104:107]
	v_mfma_f32_16x16x32_bf16 v[100:103], v[144:147], v[192:195], v[100:103]
	v_mfma_f32_16x16x32_bf16 v[96:99], v[148:151], v[164:167], v[96:99]
	v_mfma_f32_16x16x32_bf16 v[92:95], v[156:159], v[164:167], v[92:95]
	v_mfma_f32_16x16x32_bf16 v[88:91], v[148:151], v[172:175], v[88:91]
	v_mfma_f32_16x16x32_bf16 v[84:87], v[156:159], v[172:175], v[84:87]
	v_mfma_f32_16x16x32_bf16 v[80:83], v[148:151], v[180:183], v[80:83]
	v_mfma_f32_16x16x32_bf16 v[76:79], v[156:159], v[180:183], v[76:79]
	v_mfma_f32_16x16x32_bf16 v[72:75], v[148:151], v[188:191], v[72:75]
	v_mfma_f32_16x16x32_bf16 v[68:71], v[156:159], v[188:191], v[68:71]
	v_mfma_f32_16x16x32_bf16 v[96:99], v[152:155], v[168:171], v[96:99]
	v_mfma_f32_16x16x32_bf16 v[92:95], v[160:163], v[168:171], v[92:95]
	v_mfma_f32_16x16x32_bf16 v[88:91], v[152:155], v[176:179], v[88:91]
	v_mfma_f32_16x16x32_bf16 v[84:87], v[160:163], v[176:179], v[84:87]
	v_mfma_f32_16x16x32_bf16 v[80:83], v[152:155], v[184:187], v[80:83]
	v_mfma_f32_16x16x32_bf16 v[76:79], v[160:163], v[184:187], v[76:79]
	v_mfma_f32_16x16x32_bf16 v[72:75], v[152:155], v[192:195], v[72:75]
	v_mfma_f32_16x16x32_bf16 v[68:71], v[160:163], v[192:195], v[68:71]
	s_barrier
	s_add_i32 s42, s66, s15
	v_lshl_add_u64 v[6:7], v[212:213], 0, s[12:13]
	s_mov_b32 m0, s42
	ds_read_b128 v[164:167], v230 offset:49152
	ds_read_b128 v[168:171], v230 offset:50176
	ds_read_b128 v[172:175], v230 offset:51200
	ds_read_b128 v[176:179], v230 offset:52224
	ds_read_b128 v[180:183], v230 offset:53248
	ds_read_b128 v[184:187], v230 offset:54272
	ds_read_b128 v[188:191], v230 offset:55296
	ds_read_b128 v[192:195], v230 offset:56320
	global_load_lds_dwordx4 v[6:7], off
	s_add_i32 m0, s42, 0x2000
	s_add_u32 s34, s34, 0x80080
	v_lshl_add_u64 v[6:7], v[214:215], 0, s[12:13]
	s_addc_u32 s35, s35, 0
	s_add_i32 s42, s67, s15
	global_load_lds_dwordx4 v[6:7], off
	v_lshl_add_u64 v[6:7], s[34:35], 0, v[204:205]
	s_mov_b32 m0, s42
	s_nop 0
	global_load_lds_dwordx4 v[6:7], off
	v_lshl_add_u64 v[6:7], s[34:35], 0, v[200:201]
	s_add_i32 m0, s42, 0x2000
	s_nop 0
	global_load_lds_dwordx4 v[6:7], off
	v_lshl_add_u64 v[6:7], v[216:217], 0, s[12:13]
	s_mov_b32 m0, s50
	s_nop 0
	global_load_lds_dwordx4 v[6:7], off
	v_lshl_add_u64 v[6:7], v[218:219], 0, s[12:13]
	s_mov_b32 m0, s51
	s_nop 0
	global_load_lds_dwordx4 v[6:7], off
	s_waitcnt vmcnt(8)
	s_waitcnt lgkmcnt(0)
	s_barrier
	v_mfma_f32_16x16x32_bf16 v[64:67], v[132:135], v[164:167], v[64:67]
	v_mfma_f32_16x16x32_bf16 v[60:63], v[140:143], v[164:167], v[60:63]
	v_mfma_f32_16x16x32_bf16 v[56:59], v[132:135], v[172:175], v[56:59]
	v_mfma_f32_16x16x32_bf16 v[52:55], v[140:143], v[172:175], v[52:55]
	v_mfma_f32_16x16x32_bf16 v[48:51], v[132:135], v[180:183], v[48:51]
	v_mfma_f32_16x16x32_bf16 v[44:47], v[140:143], v[180:183], v[44:47]
	v_mfma_f32_16x16x32_bf16 v[40:43], v[132:135], v[188:191], v[40:43]
	v_mfma_f32_16x16x32_bf16 v[36:39], v[140:143], v[188:191], v[36:39]
	v_mfma_f32_16x16x32_bf16 v[64:67], v[136:139], v[168:171], v[64:67]
	v_mfma_f32_16x16x32_bf16 v[60:63], v[144:147], v[168:171], v[60:63]
	v_mfma_f32_16x16x32_bf16 v[56:59], v[136:139], v[176:179], v[56:59]
	v_mfma_f32_16x16x32_bf16 v[52:55], v[144:147], v[176:179], v[52:55]
	v_mfma_f32_16x16x32_bf16 v[48:51], v[136:139], v[184:187], v[48:51]
	v_mfma_f32_16x16x32_bf16 v[44:47], v[144:147], v[184:187], v[44:47]
	v_mfma_f32_16x16x32_bf16 v[40:43], v[136:139], v[192:195], v[40:43]
	v_mfma_f32_16x16x32_bf16 v[36:39], v[144:147], v[192:195], v[36:39]
	v_mfma_f32_16x16x32_bf16 v[32:35], v[148:151], v[164:167], v[32:35]
	v_mfma_f32_16x16x32_bf16 v[28:31], v[156:159], v[164:167], v[28:31]
	v_mfma_f32_16x16x32_bf16 v[24:27], v[148:151], v[172:175], v[24:27]
	v_mfma_f32_16x16x32_bf16 v[20:23], v[156:159], v[172:175], v[20:23]
	v_mfma_f32_16x16x32_bf16 v[16:19], v[148:151], v[180:183], v[16:19]
	v_mfma_f32_16x16x32_bf16 v[12:15], v[156:159], v[180:183], v[12:15]
	v_mfma_f32_16x16x32_bf16 v[6:9], v[148:151], v[188:191], v[8:11]
	v_mfma_f32_16x16x32_bf16 v[2:5], v[156:159], v[188:191], v[2:5]
	v_mfma_f32_16x16x32_bf16 v[32:35], v[152:155], v[168:171], v[32:35]
	v_mfma_f32_16x16x32_bf16 v[28:31], v[160:163], v[168:171], v[28:31]
	v_mfma_f32_16x16x32_bf16 v[24:27], v[152:155], v[176:179], v[24:27]
	v_mfma_f32_16x16x32_bf16 v[20:23], v[160:163], v[176:179], v[20:23]
	v_mfma_f32_16x16x32_bf16 v[16:19], v[152:155], v[184:187], v[16:19]
	v_mfma_f32_16x16x32_bf16 v[12:15], v[160:163], v[184:187], v[12:15]
	v_mfma_f32_16x16x32_bf16 v[8:11], v[152:155], v[192:195], v[6:9]
	v_mfma_f32_16x16x32_bf16 v[4:7], v[160:163], v[192:195], v[2:5]
	s_barrier
	s_add_i32 s57, s57, 2
	s_add_u32 s30, s30, 0x100
	s_addc_u32 s31, s31, 0
	s_add_u32 s55, s55, 0x100
	s_addc_u32 s56, s56, 0
	s_cmp_gt_u32 s57, 29
	s_cbranch_scc0 .LBB0_577
	s_and_b64 vcc, exec, s[20:21]
	s_cbranch_vccz .LBB0_580
	s_barrier

.LBB0_779:
	s_add_u32 s34, s30, 0xfff80080
	s_addc_u32 s35, s31, -1
	s_add_i32 s66, 0, 0x10000
	s_cmp_eq_u32 s57, 28
	s_cselect_b32 s43, s25, s35
	s_cselect_b32 s42, s53, s34
	s_cselect_b32 s35, s23, s56
	s_cselect_b32 s34, s54, s55
	s_add_i32 s73, 0, 0x14000
	v_add_u32_e32 v114, s66, v157
	v_add_u32_e32 v156, s73, v157
	ds_read_b128 v[90:93], v114
	ds_read_b128 v[94:97], v114 offset:1024
	ds_read_b128 v[106:109], v114 offset:2048
	ds_read_b128 v[114:117], v114 offset:3072
	ds_read_b128 v[162:165], v156
	ds_read_b128 v[166:169], v156 offset:1024
	ds_read_b128 v[170:173], v156 offset:2048
	ds_read_b128 v[174:177], v156 offset:3072
	v_lshl_add_u64 v[158:159], s[30:31], 0, v[152:153]
	s_add_i32 m0, s14, 0xc000
	ds_read_b128 v[178:181], v161
	ds_read_b128 v[182:185], v161 offset:1024
	ds_read_b128 v[186:189], v161 offset:2048
	ds_read_b128 v[190:193], v161 offset:3072
	ds_read_b128 v[200:203], v161 offset:4096
	ds_read_b128 v[204:207], v161 offset:5120
	ds_read_b128 v[208:211], v161 offset:6144
	ds_read_b128 v[212:215], v161 offset:7168
	global_load_lds_dwordx4 v[158:159], off
	v_lshl_add_u64 v[158:159], s[30:31], 0, v[154:155]
	s_add_i32 m0, s14, 0xe000
	s_nop 0
	global_load_lds_dwordx4 v[158:159], off
	s_waitcnt vmcnt(8)
	s_waitcnt lgkmcnt(0)
	s_barrier
	v_mfma_i32_16x16x64_i8 v[142:145], v[90:93], v[178:181], v[142:145]
	v_mfma_i32_16x16x64_i8 v[138:141], v[106:109], v[178:181], v[138:141]
	v_mfma_i32_16x16x64_i8 v[126:129], v[90:93], v[186:189], v[126:129]
	v_mfma_i32_16x16x64_i8 v[122:125], v[106:109], v[186:189], v[122:125]
	v_mfma_i32_16x16x64_i8 v[102:105], v[90:93], v[200:203], v[102:105]
	v_mfma_i32_16x16x64_i8 v[98:101], v[106:109], v[200:203], v[98:101]
	v_mfma_i32_16x16x64_i8 v[78:81], v[90:93], v[208:211], v[78:81]
	v_mfma_i32_16x16x64_i8 v[74:77], v[106:109], v[208:211], v[74:77]
	v_mfma_i32_16x16x64_i8 v[142:145], v[94:97], v[182:185], v[142:145]
	v_mfma_i32_16x16x64_i8 v[138:141], v[114:117], v[182:185], v[138:141]
	v_mfma_i32_16x16x64_i8 v[126:129], v[94:97], v[190:193], v[126:129]
	v_mfma_i32_16x16x64_i8 v[122:125], v[114:117], v[190:193], v[122:125]
	v_mfma_i32_16x16x64_i8 v[102:105], v[94:97], v[204:207], v[102:105]
	v_mfma_i32_16x16x64_i8 v[98:101], v[114:117], v[204:207], v[98:101]
	v_mfma_i32_16x16x64_i8 v[78:81], v[94:97], v[212:215], v[78:81]
	v_mfma_i32_16x16x64_i8 v[74:77], v[114:117], v[212:215], v[74:77]
	v_mfma_i32_16x16x64_i8 v[134:137], v[162:165], v[178:181], v[134:137]
	v_mfma_i32_16x16x64_i8 v[130:133], v[170:173], v[178:181], v[130:133]
	v_mfma_i32_16x16x64_i8 v[118:121], v[162:165], v[186:189], v[118:121]
	v_mfma_i32_16x16x64_i8 v[110:113], v[170:173], v[186:189], v[110:113]
	v_mfma_i32_16x16x64_i8 v[86:89], v[162:165], v[200:203], v[86:89]
	v_mfma_i32_16x16x64_i8 v[82:85], v[170:173], v[200:203], v[82:85]
	v_mfma_i32_16x16x64_i8 v[70:73], v[162:165], v[208:211], v[70:73]
	v_mfma_i32_16x16x64_i8 v[66:69], v[170:173], v[208:211], v[66:69]
	v_mfma_i32_16x16x64_i8 v[134:137], v[166:169], v[182:185], v[134:137]
	v_mfma_i32_16x16x64_i8 v[130:133], v[174:177], v[182:185], v[130:133]
	v_mfma_i32_16x16x64_i8 v[118:121], v[166:169], v[190:193], v[118:121]
	v_mfma_i32_16x16x64_i8 v[110:113], v[174:177], v[190:193], v[110:113]
	v_mfma_i32_16x16x64_i8 v[86:89], v[166:169], v[204:207], v[86:89]
	v_mfma_i32_16x16x64_i8 v[82:85], v[174:177], v[204:207], v[82:85]
	v_mfma_i32_16x16x64_i8 v[70:73], v[166:169], v[212:215], v[70:73]
	v_mfma_i32_16x16x64_i8 v[66:69], v[174:177], v[212:215], v[66:69]
	s_barrier
	s_add_i32 s66, s66, s9
	v_lshl_add_u64 v[158:159], s[34:35], 0, v[0:1]
	s_mov_b32 m0, s66
	ds_read_b128 v[178:181], v161 offset:16384
	ds_read_b128 v[182:185], v161 offset:17408
	ds_read_b128 v[186:189], v161 offset:18432
	ds_read_b128 v[190:193], v161 offset:19456
	ds_read_b128 v[200:203], v161 offset:20480
	ds_read_b128 v[204:207], v161 offset:21504
	ds_read_b128 v[208:211], v161 offset:22528
	ds_read_b128 v[212:215], v161 offset:23552
	global_load_lds_dwordx4 v[158:159], off
	s_add_i32 m0, s66, 0x2000
	s_add_u32 s66, s34, 0x80000
	v_lshl_add_u64 v[194:195], s[34:35], 0, v[146:147]
	s_addc_u32 s67, s35, 0
	s_add_i32 s73, s73, s9
	global_load_lds_dwordx4 v[194:195], off
	v_lshl_add_u64 v[216:217], s[66:67], 0, v[0:1]
	s_mov_b32 m0, s73
	v_lshl_add_u64 v[218:219], s[42:43], 0, v[148:149]
	global_load_lds_dwordx4 v[216:217], off
	v_lshl_add_u64 v[216:217], s[66:67], 0, v[146:147]
	s_add_i32 m0, s73, 0x2000
	s_nop 0
	global_load_lds_dwordx4 v[216:217], off
	v_lshl_add_u64 v[216:217], s[42:43], 0, v[150:151]
	s_mov_b32 m0, s14
	s_nop 0
	global_load_lds_dwordx4 v[216:217], off
	s_mov_b32 m0, s15
	s_nop 0
	global_load_lds_dwordx4 v[218:219], off
	s_waitcnt vmcnt(8)
	s_waitcnt lgkmcnt(0)
	s_barrier
	v_mfma_i32_16x16x64_i8 v[62:65], v[90:93], v[178:181], v[62:65]
	v_mfma_i32_16x16x64_i8 v[58:61], v[106:109], v[178:181], v[58:61]
	v_mfma_i32_16x16x64_i8 v[46:49], v[90:93], v[186:189], v[46:49]
	v_mfma_i32_16x16x64_i8 v[42:45], v[106:109], v[186:189], v[42:45]
	v_mfma_i32_16x16x64_i8 v[30:33], v[90:93], v[200:203], v[30:33]
	v_mfma_i32_16x16x64_i8 v[26:29], v[106:109], v[200:203], v[26:29]
	v_mfma_i32_16x16x64_i8 v[14:17], v[90:93], v[208:211], v[14:17]
	v_mfma_i32_16x16x64_i8 v[10:13], v[106:109], v[208:211], v[10:13]
	v_mfma_i32_16x16x64_i8 v[62:65], v[94:97], v[182:185], v[62:65]
	v_mfma_i32_16x16x64_i8 v[58:61], v[114:117], v[182:185], v[58:61]
	v_mfma_i32_16x16x64_i8 v[46:49], v[94:97], v[190:193], v[46:49]
	v_mfma_i32_16x16x64_i8 v[42:45], v[114:117], v[190:193], v[42:45]
	v_mfma_i32_16x16x64_i8 v[30:33], v[94:97], v[204:207], v[30:33]
	v_mfma_i32_16x16x64_i8 v[26:29], v[114:117], v[204:207], v[26:29]
	v_mfma_i32_16x16x64_i8 v[14:17], v[94:97], v[212:215], v[14:17]
	v_mfma_i32_16x16x64_i8 v[10:13], v[114:117], v[212:215], v[10:13]
	v_mfma_i32_16x16x64_i8 v[54:57], v[162:165], v[178:181], v[54:57]
	v_mfma_i32_16x16x64_i8 v[50:53], v[170:173], v[178:181], v[50:53]
	v_mfma_i32_16x16x64_i8 v[38:41], v[162:165], v[186:189], v[38:41]
	v_mfma_i32_16x16x64_i8 v[34:37], v[170:173], v[186:189], v[34:37]
	v_mfma_i32_16x16x64_i8 v[22:25], v[162:165], v[200:203], v[22:25]
	v_mfma_i32_16x16x64_i8 v[18:21], v[170:173], v[200:203], v[18:21]
	v_mfma_i32_16x16x64_i8 v[6:9], v[162:165], v[208:211], v[6:9]
	v_mfma_i32_16x16x64_i8 v[2:5], v[170:173], v[208:211], v[2:5]
	v_mfma_i32_16x16x64_i8 v[54:57], v[166:169], v[182:185], v[54:57]
	v_mfma_i32_16x16x64_i8 v[50:53], v[174:177], v[182:185], v[50:53]
	v_mfma_i32_16x16x64_i8 v[38:41], v[166:169], v[190:193], v[38:41]
	v_mfma_i32_16x16x64_i8 v[34:37], v[174:177], v[190:193], v[34:37]
	v_mfma_i32_16x16x64_i8 v[22:25], v[166:169], v[204:207], v[22:25]
	v_mfma_i32_16x16x64_i8 v[18:21], v[174:177], v[204:207], v[18:21]
	v_mfma_i32_16x16x64_i8 v[6:9], v[166:169], v[212:215], v[6:9]
	v_mfma_i32_16x16x64_i8 v[2:5], v[174:177], v[212:215], v[2:5]
	s_barrier
	s_add_i32 s66, 0, 0x18000
	s_add_i32 s67, 0, 0x1c000
	v_add_u32_e32 v114, s66, v157
	v_add_u32_e32 v156, s67, v157
	ds_read_b128 v[90:93], v114
	ds_read_b128 v[94:97], v114 offset:1024
	ds_read_b128 v[106:109], v114 offset:2048
	ds_read_b128 v[114:117], v114 offset:3072
	ds_read_b128 v[162:165], v156
	ds_read_b128 v[166:169], v156 offset:1024
	ds_read_b128 v[170:173], v156 offset:2048
	ds_read_b128 v[174:177], v156 offset:3072
	s_add_u32 s42, s42, 0x80000
	s_addc_u32 s43, s43, 0
	s_mov_b32 m0, s46
	v_lshl_add_u64 v[220:221], s[42:43], 0, v[150:151]
	ds_read_b128 v[178:181], v161 offset:32768
	ds_read_b128 v[182:185], v161 offset:33792
	ds_read_b128 v[186:189], v161 offset:34816
	ds_read_b128 v[190:193], v161 offset:35840
	ds_read_b128 v[200:203], v161 offset:36864
	ds_read_b128 v[204:207], v161 offset:37888
	ds_read_b128 v[208:211], v161 offset:38912
	ds_read_b128 v[212:215], v161 offset:39936
	global_load_lds_dwordx4 v[220:221], off
	v_lshl_add_u64 v[220:221], s[42:43], 0, v[148:149]
	s_mov_b32 m0, s47
	s_nop 0
	global_load_lds_dwordx4 v[220:221], off
	s_waitcnt vmcnt(8)
	s_waitcnt lgkmcnt(0)
	s_barrier
	v_mfma_i32_16x16x64_i8 v[142:145], v[90:93], v[178:181], v[142:145]
	v_mfma_i32_16x16x64_i8 v[138:141], v[106:109], v[178:181], v[138:141]
	v_mfma_i32_16x16x64_i8 v[126:129], v[90:93], v[186:189], v[126:129]
	v_mfma_i32_16x16x64_i8 v[122:125], v[106:109], v[186:189], v[122:125]
	v_mfma_i32_16x16x64_i8 v[102:105], v[90:93], v[200:203], v[102:105]
	v_mfma_i32_16x16x64_i8 v[98:101], v[106:109], v[200:203], v[98:101]
	v_mfma_i32_16x16x64_i8 v[78:81], v[90:93], v[208:211], v[78:81]
	v_mfma_i32_16x16x64_i8 v[74:77], v[106:109], v[208:211], v[74:77]
	v_mfma_i32_16x16x64_i8 v[142:145], v[94:97], v[182:185], v[142:145]
	v_mfma_i32_16x16x64_i8 v[138:141], v[114:117], v[182:185], v[138:141]
	v_mfma_i32_16x16x64_i8 v[126:129], v[94:97], v[190:193], v[126:129]
	v_mfma_i32_16x16x64_i8 v[122:125], v[114:117], v[190:193], v[122:125]
	v_mfma_i32_16x16x64_i8 v[102:105], v[94:97], v[204:207], v[102:105]
	v_mfma_i32_16x16x64_i8 v[98:101], v[114:117], v[204:207], v[98:101]
	v_mfma_i32_16x16x64_i8 v[78:81], v[94:97], v[212:215], v[78:81]
	v_mfma_i32_16x16x64_i8 v[74:77], v[114:117], v[212:215], v[74:77]
	v_mfma_i32_16x16x64_i8 v[134:137], v[162:165], v[178:181], v[134:137]
	v_mfma_i32_16x16x64_i8 v[130:133], v[170:173], v[178:181], v[130:133]
	v_mfma_i32_16x16x64_i8 v[118:121], v[162:165], v[186:189], v[118:121]
	v_mfma_i32_16x16x64_i8 v[110:113], v[170:173], v[186:189], v[110:113]
	v_mfma_i32_16x16x64_i8 v[86:89], v[162:165], v[200:203], v[86:89]
	v_mfma_i32_16x16x64_i8 v[82:85], v[170:173], v[200:203], v[82:85]
	v_mfma_i32_16x16x64_i8 v[70:73], v[162:165], v[208:211], v[70:73]
	v_mfma_i32_16x16x64_i8 v[66:69], v[170:173], v[208:211], v[66:69]
	v_mfma_i32_16x16x64_i8 v[134:137], v[166:169], v[182:185], v[134:137]
	v_mfma_i32_16x16x64_i8 v[130:133], v[174:177], v[182:185], v[130:133]
	v_mfma_i32_16x16x64_i8 v[118:121], v[166:169], v[190:193], v[118:121]
	v_mfma_i32_16x16x64_i8 v[110:113], v[174:177], v[190:193], v[110:113]
	v_mfma_i32_16x16x64_i8 v[86:89], v[166:169], v[204:207], v[86:89]
	v_mfma_i32_16x16x64_i8 v[82:85], v[174:177], v[204:207], v[82:85]
	v_mfma_i32_16x16x64_i8 v[70:73], v[166:169], v[212:215], v[70:73]
	v_mfma_i32_16x16x64_i8 v[66:69], v[174:177], v[212:215], v[66:69]
	s_barrier
	s_add_i32 s42, s66, s9
	v_lshl_add_u64 v[158:159], v[158:159], 0, s[12:13]
	s_mov_b32 m0, s42
	ds_read_b128 v[178:181], v161 offset:49152
	ds_read_b128 v[182:185], v161 offset:50176
	ds_read_b128 v[186:189], v161 offset:51200
	ds_read_b128 v[190:193], v161 offset:52224
	ds_read_b128 v[200:203], v161 offset:53248
	ds_read_b128 v[204:207], v161 offset:54272
	ds_read_b128 v[208:211], v161 offset:55296
	ds_read_b128 v[212:215], v161 offset:56320
	global_load_lds_dwordx4 v[158:159], off
	s_add_i32 m0, s42, 0x2000
	s_add_u32 s34, s34, 0x80080
	v_lshl_add_u64 v[158:159], v[194:195], 0, s[12:13]
	s_addc_u32 s35, s35, 0
	s_add_i32 s42, s67, s9
	global_load_lds_dwordx4 v[158:159], off
	v_lshl_add_u64 v[158:159], s[34:35], 0, v[0:1]
	s_mov_b32 m0, s42
	s_nop 0
	global_load_lds_dwordx4 v[158:159], off
	v_lshl_add_u64 v[158:159], s[34:35], 0, v[146:147]
	s_add_i32 m0, s42, 0x2000
	s_nop 0
	global_load_lds_dwordx4 v[158:159], off
	v_lshl_add_u64 v[158:159], v[216:217], 0, s[12:13]
	s_mov_b32 m0, s50
	s_nop 0
	global_load_lds_dwordx4 v[158:159], off
	v_lshl_add_u64 v[158:159], v[218:219], 0, s[12:13]
	s_mov_b32 m0, s51
	s_nop 0
	global_load_lds_dwordx4 v[158:159], off
	s_waitcnt vmcnt(8)
	s_waitcnt lgkmcnt(0)
	s_barrier
	v_mfma_i32_16x16x64_i8 v[62:65], v[90:93], v[178:181], v[62:65]
	v_mfma_i32_16x16x64_i8 v[58:61], v[106:109], v[178:181], v[58:61]
	v_mfma_i32_16x16x64_i8 v[46:49], v[90:93], v[186:189], v[46:49]
	v_mfma_i32_16x16x64_i8 v[42:45], v[106:109], v[186:189], v[42:45]
	v_mfma_i32_16x16x64_i8 v[30:33], v[90:93], v[200:203], v[30:33]
	v_mfma_i32_16x16x64_i8 v[26:29], v[106:109], v[200:203], v[26:29]
	v_mfma_i32_16x16x64_i8 v[14:17], v[90:93], v[208:211], v[14:17]
	v_mfma_i32_16x16x64_i8 v[10:13], v[106:109], v[208:211], v[10:13]
	v_mfma_i32_16x16x64_i8 v[62:65], v[94:97], v[182:185], v[62:65]
	v_mfma_i32_16x16x64_i8 v[58:61], v[114:117], v[182:185], v[58:61]
	v_mfma_i32_16x16x64_i8 v[46:49], v[94:97], v[190:193], v[46:49]
	v_mfma_i32_16x16x64_i8 v[42:45], v[114:117], v[190:193], v[42:45]
	v_mfma_i32_16x16x64_i8 v[30:33], v[94:97], v[204:207], v[30:33]
	v_mfma_i32_16x16x64_i8 v[26:29], v[114:117], v[204:207], v[26:29]
	v_mfma_i32_16x16x64_i8 v[14:17], v[94:97], v[212:215], v[14:17]
	v_mfma_i32_16x16x64_i8 v[10:13], v[114:117], v[212:215], v[10:13]
	v_mfma_i32_16x16x64_i8 v[54:57], v[162:165], v[178:181], v[54:57]
	v_mfma_i32_16x16x64_i8 v[50:53], v[170:173], v[178:181], v[50:53]
	v_mfma_i32_16x16x64_i8 v[38:41], v[162:165], v[186:189], v[38:41]
	v_mfma_i32_16x16x64_i8 v[34:37], v[170:173], v[186:189], v[34:37]
	v_mfma_i32_16x16x64_i8 v[22:25], v[162:165], v[200:203], v[22:25]
	v_mfma_i32_16x16x64_i8 v[18:21], v[170:173], v[200:203], v[18:21]
	v_mfma_i32_16x16x64_i8 v[6:9], v[162:165], v[208:211], v[6:9]
	v_mfma_i32_16x16x64_i8 v[2:5], v[170:173], v[208:211], v[2:5]
	v_mfma_i32_16x16x64_i8 v[54:57], v[166:169], v[182:185], v[54:57]
	v_mfma_i32_16x16x64_i8 v[50:53], v[174:177], v[182:185], v[50:53]
	v_mfma_i32_16x16x64_i8 v[38:41], v[166:169], v[190:193], v[38:41]
	v_mfma_i32_16x16x64_i8 v[34:37], v[174:177], v[190:193], v[34:37]
	v_mfma_i32_16x16x64_i8 v[22:25], v[166:169], v[204:207], v[22:25]
	v_mfma_i32_16x16x64_i8 v[18:21], v[174:177], v[204:207], v[18:21]
	v_mfma_i32_16x16x64_i8 v[6:9], v[166:169], v[212:215], v[6:9]
	v_mfma_i32_16x16x64_i8 v[2:5], v[174:177], v[212:215], v[2:5]
	s_barrier
	s_add_i32 s57, s57, 2
	s_add_u32 s30, s30, 0x100
	s_addc_u32 s31, s31, 0
	s_add_u32 s55, s55, 0x100
	s_addc_u32 s56, s56, 0
	s_cmp_gt_u32 s57, 29
	s_cbranch_scc0 .LBB0_779
	s_and_b64 vcc, exec, s[20:21]
	s_mov_b32 s54, 0x5c401000
	s_cbranch_vccz .LBB0_782
	s_barrier

.LBB0_801:
	s_add_u32 s34, s30, 0xfff00080
	s_addc_u32 s35, s31, -1
	s_add_i32 s54, 0, 0x10000
	s_cmp_eq_u32 s53, 60
	s_cselect_b32 s41, s25, s35
	s_cselect_b32 s40, s49, s34
	s_cselect_b32 s35, s23, s52
	s_cselect_b32 s34, s50, s51
	s_add_i32 s56, 0, 0x14000
	v_add_u32_e32 v156, s54, v141
	v_add_u32_e32 v172, s56, v141
	ds_read_b128 v[144:147], v156
	ds_read_b128 v[148:151], v156 offset:1024
	ds_read_b128 v[152:155], v156 offset:2048
	ds_read_b128 v[156:159], v156 offset:3072
	ds_read_b128 v[160:163], v172
	ds_read_b128 v[164:167], v172 offset:1024
	ds_read_b128 v[168:171], v172 offset:2048
	ds_read_b128 v[172:175], v172 offset:3072
	v_lshl_add_u64 v[212:213], s[30:31], 0, v[136:137]
	s_add_i32 m0, s14, 0xc000
	ds_read_b128 v[176:179], v143
	ds_read_b128 v[180:183], v143 offset:1024
	ds_read_b128 v[184:187], v143 offset:2048
	ds_read_b128 v[188:191], v143 offset:3072
	ds_read_b128 v[192:195], v143 offset:4096
	ds_read_b128 v[200:203], v143 offset:5120
	ds_read_b128 v[204:207], v143 offset:6144
	ds_read_b128 v[208:211], v143 offset:7168
	global_load_lds_dwordx4 v[212:213], off
	v_lshl_add_u64 v[212:213], s[30:31], 0, v[138:139]
	s_add_i32 m0, s14, 0xe000
	s_nop 0
	global_load_lds_dwordx4 v[212:213], off
	s_waitcnt vmcnt(8)
	s_waitcnt lgkmcnt(0)
	s_barrier
	v_mfma_f32_16x16x32_bf16 v[126:129], v[144:147], v[176:179], v[126:129]
	v_mfma_f32_16x16x32_bf16 v[122:125], v[152:155], v[176:179], v[122:125]
	v_mfma_f32_16x16x32_bf16 v[118:121], v[144:147], v[184:187], v[118:121]
	v_mfma_f32_16x16x32_bf16 v[114:117], v[152:155], v[184:187], v[114:117]
	v_mfma_f32_16x16x32_bf16 v[102:105], v[144:147], v[192:195], v[102:105]
	v_mfma_f32_16x16x32_bf16 v[98:101], v[152:155], v[192:195], v[98:101]
	v_mfma_f32_16x16x32_bf16 v[86:89], v[144:147], v[204:207], v[86:89]
	v_mfma_f32_16x16x32_bf16 v[82:85], v[152:155], v[204:207], v[82:85]
	v_mfma_f32_16x16x32_bf16 v[126:129], v[148:151], v[180:183], v[126:129]
	v_mfma_f32_16x16x32_bf16 v[122:125], v[156:159], v[180:183], v[122:125]
	v_mfma_f32_16x16x32_bf16 v[118:121], v[148:151], v[188:191], v[118:121]
	v_mfma_f32_16x16x32_bf16 v[114:117], v[156:159], v[188:191], v[114:117]
	v_mfma_f32_16x16x32_bf16 v[102:105], v[148:151], v[200:203], v[102:105]
	v_mfma_f32_16x16x32_bf16 v[98:101], v[156:159], v[200:203], v[98:101]
	v_mfma_f32_16x16x32_bf16 v[86:89], v[148:151], v[208:211], v[86:89]
	v_mfma_f32_16x16x32_bf16 v[82:85], v[156:159], v[208:211], v[82:85]
	v_mfma_f32_16x16x32_bf16 v[110:113], v[160:163], v[176:179], v[110:113]
	v_mfma_f32_16x16x32_bf16 v[106:109], v[168:171], v[176:179], v[106:109]
	v_mfma_f32_16x16x32_bf16 v[94:97], v[160:163], v[184:187], v[94:97]
	v_mfma_f32_16x16x32_bf16 v[90:93], v[168:171], v[184:187], v[90:93]
	v_mfma_f32_16x16x32_bf16 v[78:81], v[160:163], v[192:195], v[78:81]
	v_mfma_f32_16x16x32_bf16 v[74:77], v[168:171], v[192:195], v[74:77]
	v_mfma_f32_16x16x32_bf16 v[70:73], v[160:163], v[204:207], v[70:73]
	v_mfma_f32_16x16x32_bf16 v[66:69], v[168:171], v[204:207], v[66:69]
	v_mfma_f32_16x16x32_bf16 v[110:113], v[164:167], v[180:183], v[110:113]
	v_mfma_f32_16x16x32_bf16 v[106:109], v[172:175], v[180:183], v[106:109]
	v_mfma_f32_16x16x32_bf16 v[94:97], v[164:167], v[188:191], v[94:97]
	v_mfma_f32_16x16x32_bf16 v[90:93], v[172:175], v[188:191], v[90:93]
	v_mfma_f32_16x16x32_bf16 v[78:81], v[164:167], v[200:203], v[78:81]
	v_mfma_f32_16x16x32_bf16 v[74:77], v[172:175], v[200:203], v[74:77]
	v_mfma_f32_16x16x32_bf16 v[70:73], v[164:167], v[208:211], v[70:73]
	v_mfma_f32_16x16x32_bf16 v[66:69], v[172:175], v[208:211], v[66:69]
	s_barrier
	s_add_i32 s54, s54, s9
	v_lshl_add_u64 v[212:213], s[34:35], 0, v[0:1]
	s_mov_b32 m0, s54
	ds_read_b128 v[176:179], v143 offset:16384
	ds_read_b128 v[180:183], v143 offset:17408
	ds_read_b128 v[184:187], v143 offset:18432
	ds_read_b128 v[188:191], v143 offset:19456
	ds_read_b128 v[192:195], v143 offset:20480
	ds_read_b128 v[200:203], v143 offset:21504
	ds_read_b128 v[204:207], v143 offset:22528
	ds_read_b128 v[208:211], v143 offset:23552
	global_load_lds_dwordx4 v[212:213], off
	s_add_i32 m0, s54, 0x2000
	s_add_u32 s54, s34, 0x100000
	v_lshl_add_u64 v[214:215], s[34:35], 0, v[130:131]
	s_addc_u32 s55, s35, 0
	s_add_i32 s56, s56, s9
	global_load_lds_dwordx4 v[214:215], off
	v_lshl_add_u64 v[216:217], s[54:55], 0, v[0:1]
	s_mov_b32 m0, s56
	v_lshl_add_u64 v[218:219], s[40:41], 0, v[132:133]
	global_load_lds_dwordx4 v[216:217], off
	v_lshl_add_u64 v[216:217], s[54:55], 0, v[130:131]
	s_add_i32 m0, s56, 0x2000
	s_nop 0
	global_load_lds_dwordx4 v[216:217], off
	v_lshl_add_u64 v[216:217], s[40:41], 0, v[134:135]
	s_mov_b32 m0, s14
	s_nop 0
	global_load_lds_dwordx4 v[216:217], off
	s_mov_b32 m0, s15
	s_nop 0
	global_load_lds_dwordx4 v[218:219], off
	s_waitcnt vmcnt(8)
	s_waitcnt lgkmcnt(0)
	s_barrier
	v_mfma_f32_16x16x32_bf16 v[62:65], v[144:147], v[176:179], v[62:65]
	v_mfma_f32_16x16x32_bf16 v[58:61], v[152:155], v[176:179], v[58:61]
	v_mfma_f32_16x16x32_bf16 v[54:57], v[144:147], v[184:187], v[54:57]
	v_mfma_f32_16x16x32_bf16 v[50:53], v[152:155], v[184:187], v[50:53]
	v_mfma_f32_16x16x32_bf16 v[38:41], v[144:147], v[192:195], v[38:41]
	v_mfma_f32_16x16x32_bf16 v[34:37], v[152:155], v[192:195], v[34:37]
	v_mfma_f32_16x16x32_bf16 v[22:25], v[144:147], v[204:207], v[22:25]
	v_mfma_f32_16x16x32_bf16 v[18:21], v[152:155], v[204:207], v[18:21]
	v_mfma_f32_16x16x32_bf16 v[62:65], v[148:151], v[180:183], v[62:65]
	v_mfma_f32_16x16x32_bf16 v[58:61], v[156:159], v[180:183], v[58:61]
	v_mfma_f32_16x16x32_bf16 v[54:57], v[148:151], v[188:191], v[54:57]
	v_mfma_f32_16x16x32_bf16 v[50:53], v[156:159], v[188:191], v[50:53]
	v_mfma_f32_16x16x32_bf16 v[38:41], v[148:151], v[200:203], v[38:41]
	v_mfma_f32_16x16x32_bf16 v[34:37], v[156:159], v[200:203], v[34:37]
	v_mfma_f32_16x16x32_bf16 v[22:25], v[148:151], v[208:211], v[22:25]
	v_mfma_f32_16x16x32_bf16 v[18:21], v[156:159], v[208:211], v[18:21]
	v_mfma_f32_16x16x32_bf16 v[46:49], v[160:163], v[176:179], v[46:49]
	v_mfma_f32_16x16x32_bf16 v[42:45], v[168:171], v[176:179], v[42:45]
	v_mfma_f32_16x16x32_bf16 v[30:33], v[160:163], v[184:187], v[30:33]
	v_mfma_f32_16x16x32_bf16 v[26:29], v[168:171], v[184:187], v[26:29]
	v_mfma_f32_16x16x32_bf16 v[14:17], v[160:163], v[192:195], v[14:17]
	v_mfma_f32_16x16x32_bf16 v[10:13], v[168:171], v[192:195], v[10:13]
	v_mfma_f32_16x16x32_bf16 v[6:9], v[160:163], v[204:207], v[6:9]
	v_mfma_f32_16x16x32_bf16 v[2:5], v[168:171], v[204:207], v[2:5]
	v_mfma_f32_16x16x32_bf16 v[46:49], v[164:167], v[180:183], v[46:49]
	v_mfma_f32_16x16x32_bf16 v[42:45], v[172:175], v[180:183], v[42:45]
	v_mfma_f32_16x16x32_bf16 v[30:33], v[164:167], v[188:191], v[30:33]
	v_mfma_f32_16x16x32_bf16 v[26:29], v[172:175], v[188:191], v[26:29]
	v_mfma_f32_16x16x32_bf16 v[14:17], v[164:167], v[200:203], v[14:17]
	v_mfma_f32_16x16x32_bf16 v[10:13], v[172:175], v[200:203], v[10:13]
	v_mfma_f32_16x16x32_bf16 v[6:9], v[164:167], v[208:211], v[6:9]
	v_mfma_f32_16x16x32_bf16 v[2:5], v[172:175], v[208:211], v[2:5]
	s_barrier
	s_add_i32 s54, 0, 0x18000
	s_add_i32 s55, 0, 0x1c000
	v_add_u32_e32 v156, s54, v141
	v_add_u32_e32 v172, s55, v141
	ds_read_b128 v[144:147], v156
	ds_read_b128 v[148:151], v156 offset:1024
	ds_read_b128 v[152:155], v156 offset:2048
	ds_read_b128 v[156:159], v156 offset:3072
	ds_read_b128 v[160:163], v172
	ds_read_b128 v[164:167], v172 offset:1024
	ds_read_b128 v[168:171], v172 offset:2048
	ds_read_b128 v[172:175], v172 offset:3072
	s_add_u32 s40, s40, 0x100000
	s_addc_u32 s41, s41, 0
	s_mov_b32 m0, s18
	v_lshl_add_u64 v[220:221], s[40:41], 0, v[134:135]
	ds_read_b128 v[176:179], v143 offset:32768
	ds_read_b128 v[180:183], v143 offset:33792
	ds_read_b128 v[184:187], v143 offset:34816
	ds_read_b128 v[188:191], v143 offset:35840
	ds_read_b128 v[192:195], v143 offset:36864
	ds_read_b128 v[200:203], v143 offset:37888
	ds_read_b128 v[204:207], v143 offset:38912
	ds_read_b128 v[208:211], v143 offset:39936
	global_load_lds_dwordx4 v[220:221], off
	v_lshl_add_u64 v[220:221], s[40:41], 0, v[132:133]
	s_mov_b32 m0, s19
	s_nop 0
	global_load_lds_dwordx4 v[220:221], off
	s_waitcnt vmcnt(8)
	s_waitcnt lgkmcnt(0)
	s_barrier
	v_mfma_f32_16x16x32_bf16 v[126:129], v[144:147], v[176:179], v[126:129]
	v_mfma_f32_16x16x32_bf16 v[122:125], v[152:155], v[176:179], v[122:125]
	v_mfma_f32_16x16x32_bf16 v[118:121], v[144:147], v[184:187], v[118:121]
	v_mfma_f32_16x16x32_bf16 v[114:117], v[152:155], v[184:187], v[114:117]
	v_mfma_f32_16x16x32_bf16 v[102:105], v[144:147], v[192:195], v[102:105]
	v_mfma_f32_16x16x32_bf16 v[98:101], v[152:155], v[192:195], v[98:101]
	v_mfma_f32_16x16x32_bf16 v[86:89], v[144:147], v[204:207], v[86:89]
	v_mfma_f32_16x16x32_bf16 v[82:85], v[152:155], v[204:207], v[82:85]
	v_mfma_f32_16x16x32_bf16 v[126:129], v[148:151], v[180:183], v[126:129]
	v_mfma_f32_16x16x32_bf16 v[122:125], v[156:159], v[180:183], v[122:125]
	v_mfma_f32_16x16x32_bf16 v[118:121], v[148:151], v[188:191], v[118:121]
	v_mfma_f32_16x16x32_bf16 v[114:117], v[156:159], v[188:191], v[114:117]
	v_mfma_f32_16x16x32_bf16 v[102:105], v[148:151], v[200:203], v[102:105]
	v_mfma_f32_16x16x32_bf16 v[98:101], v[156:159], v[200:203], v[98:101]
	v_mfma_f32_16x16x32_bf16 v[86:89], v[148:151], v[208:211], v[86:89]
	v_mfma_f32_16x16x32_bf16 v[82:85], v[156:159], v[208:211], v[82:85]
	v_mfma_f32_16x16x32_bf16 v[110:113], v[160:163], v[176:179], v[110:113]
	v_mfma_f32_16x16x32_bf16 v[106:109], v[168:171], v[176:179], v[106:109]
	v_mfma_f32_16x16x32_bf16 v[94:97], v[160:163], v[184:187], v[94:97]
	v_mfma_f32_16x16x32_bf16 v[90:93], v[168:171], v[184:187], v[90:93]
	v_mfma_f32_16x16x32_bf16 v[78:81], v[160:163], v[192:195], v[78:81]
	v_mfma_f32_16x16x32_bf16 v[74:77], v[168:171], v[192:195], v[74:77]
	v_mfma_f32_16x16x32_bf16 v[70:73], v[160:163], v[204:207], v[70:73]
	v_mfma_f32_16x16x32_bf16 v[66:69], v[168:171], v[204:207], v[66:69]
	v_mfma_f32_16x16x32_bf16 v[110:113], v[164:167], v[180:183], v[110:113]
	v_mfma_f32_16x16x32_bf16 v[106:109], v[172:175], v[180:183], v[106:109]
	v_mfma_f32_16x16x32_bf16 v[94:97], v[164:167], v[188:191], v[94:97]
	v_mfma_f32_16x16x32_bf16 v[90:93], v[172:175], v[188:191], v[90:93]
	v_mfma_f32_16x16x32_bf16 v[78:81], v[164:167], v[200:203], v[78:81]
	v_mfma_f32_16x16x32_bf16 v[74:77], v[172:175], v[200:203], v[74:77]
	v_mfma_f32_16x16x32_bf16 v[70:73], v[164:167], v[208:211], v[70:73]
	v_mfma_f32_16x16x32_bf16 v[66:69], v[172:175], v[208:211], v[66:69]
	s_barrier
	s_add_i32 s40, s54, s9
	v_lshl_add_u64 v[212:213], v[212:213], 0, s[12:13]
	s_mov_b32 m0, s40
	ds_read_b128 v[176:179], v143 offset:49152
	ds_read_b128 v[180:183], v143 offset:50176
	ds_read_b128 v[184:187], v143 offset:51200
	ds_read_b128 v[188:191], v143 offset:52224
	ds_read_b128 v[192:195], v143 offset:53248
	ds_read_b128 v[200:203], v143 offset:54272
	ds_read_b128 v[204:207], v143 offset:55296
	ds_read_b128 v[208:211], v143 offset:56320
	global_load_lds_dwordx4 v[212:213], off
	s_add_i32 m0, s40, 0x2000
	s_add_u32 s34, s34, 0x100080
	v_lshl_add_u64 v[212:213], v[214:215], 0, s[12:13]
	s_addc_u32 s35, s35, 0
	s_add_i32 s40, s55, s9
	global_load_lds_dwordx4 v[212:213], off
	v_lshl_add_u64 v[212:213], s[34:35], 0, v[0:1]
	s_mov_b32 m0, s40
	s_nop 0
	global_load_lds_dwordx4 v[212:213], off
	v_lshl_add_u64 v[212:213], s[34:35], 0, v[130:131]
	s_add_i32 m0, s40, 0x2000
	s_nop 0
	global_load_lds_dwordx4 v[212:213], off
	v_lshl_add_u64 v[212:213], v[216:217], 0, s[12:13]
	s_mov_b32 m0, s42
	s_nop 0
	global_load_lds_dwordx4 v[212:213], off
	v_lshl_add_u64 v[212:213], v[218:219], 0, s[12:13]
	s_mov_b32 m0, s43
	s_nop 0
	global_load_lds_dwordx4 v[212:213], off
	s_waitcnt vmcnt(8)
	s_waitcnt lgkmcnt(0)
	s_barrier
	v_mfma_f32_16x16x32_bf16 v[62:65], v[144:147], v[176:179], v[62:65]
	v_mfma_f32_16x16x32_bf16 v[58:61], v[152:155], v[176:179], v[58:61]
	v_mfma_f32_16x16x32_bf16 v[54:57], v[144:147], v[184:187], v[54:57]
	v_mfma_f32_16x16x32_bf16 v[50:53], v[152:155], v[184:187], v[50:53]
	v_mfma_f32_16x16x32_bf16 v[38:41], v[144:147], v[192:195], v[38:41]
	v_mfma_f32_16x16x32_bf16 v[34:37], v[152:155], v[192:195], v[34:37]
	v_mfma_f32_16x16x32_bf16 v[22:25], v[144:147], v[204:207], v[22:25]
	v_mfma_f32_16x16x32_bf16 v[18:21], v[152:155], v[204:207], v[18:21]
	v_mfma_f32_16x16x32_bf16 v[62:65], v[148:151], v[180:183], v[62:65]
	v_mfma_f32_16x16x32_bf16 v[58:61], v[156:159], v[180:183], v[58:61]
	v_mfma_f32_16x16x32_bf16 v[54:57], v[148:151], v[188:191], v[54:57]
	v_mfma_f32_16x16x32_bf16 v[50:53], v[156:159], v[188:191], v[50:53]
	v_mfma_f32_16x16x32_bf16 v[38:41], v[148:151], v[200:203], v[38:41]
	v_mfma_f32_16x16x32_bf16 v[34:37], v[156:159], v[200:203], v[34:37]
	v_mfma_f32_16x16x32_bf16 v[22:25], v[148:151], v[208:211], v[22:25]
	v_mfma_f32_16x16x32_bf16 v[18:21], v[156:159], v[208:211], v[18:21]
	v_mfma_f32_16x16x32_bf16 v[46:49], v[160:163], v[176:179], v[46:49]
	v_mfma_f32_16x16x32_bf16 v[42:45], v[168:171], v[176:179], v[42:45]
	v_mfma_f32_16x16x32_bf16 v[30:33], v[160:163], v[184:187], v[30:33]
	v_mfma_f32_16x16x32_bf16 v[26:29], v[168:171], v[184:187], v[26:29]
	v_mfma_f32_16x16x32_bf16 v[14:17], v[160:163], v[192:195], v[14:17]
	v_mfma_f32_16x16x32_bf16 v[10:13], v[168:171], v[192:195], v[10:13]
	v_mfma_f32_16x16x32_bf16 v[6:9], v[160:163], v[204:207], v[6:9]
	v_mfma_f32_16x16x32_bf16 v[2:5], v[168:171], v[204:207], v[2:5]
	v_mfma_f32_16x16x32_bf16 v[46:49], v[164:167], v[180:183], v[46:49]
	v_mfma_f32_16x16x32_bf16 v[42:45], v[172:175], v[180:183], v[42:45]
	v_mfma_f32_16x16x32_bf16 v[30:33], v[164:167], v[188:191], v[30:33]
	v_mfma_f32_16x16x32_bf16 v[26:29], v[172:175], v[188:191], v[26:29]
	v_mfma_f32_16x16x32_bf16 v[14:17], v[164:167], v[200:203], v[14:17]
	v_mfma_f32_16x16x32_bf16 v[10:13], v[172:175], v[200:203], v[10:13]
	v_mfma_f32_16x16x32_bf16 v[6:9], v[164:167], v[208:211], v[6:9]
	v_mfma_f32_16x16x32_bf16 v[2:5], v[172:175], v[208:211], v[2:5]
	s_barrier
	s_add_i32 s53, s53, 2
	s_add_u32 s30, s30, 0x100
	s_addc_u32 s31, s31, 0
	s_add_u32 s51, s51, 0x100
	s_addc_u32 s52, s52, 0
	s_cmp_gt_u32 s53, 61
	s_cbranch_scc0 .LBB0_801
	s_and_b64 vcc, exec, s[20:21]
	s_cbranch_vccz .LBB0_804
	s_barrier
